# merge vmcnt+lgkmcnt waits before in-loop barriers into one s_waitcnt; drop redundant lgkmcnt(0) after s_setprio 1 in the 4 GEMM K-loops
# speedup vs baseline: 1.0029x; 1.0029x over previous
; #define PG8_STAGE(bufoff, gbase, voff) do { _Pragma("unroll") for (int _i = 0; _i < 2; ++_i) \
;         __builtin_amdgcn_global_load_lds((const unsigned*)((const char*)(gbase) + (voff)[_i]), (PG8_LAS unsigned*)(lds + (bufoff) + ldsw + _i * 8192), 16, 0, 0); } while (0)
; #define PG8_LDA(dst, b, h) do { _Pragma("unroll") for (int m = 0; m < 4; ++m) _Pragma("unroll") for (int k = 0; k < 2; ++k) dst[m][k] = *(const PG8_LAS bf16x8*)(lds + PG8_SA(b, h) + aoff + m * 2048 + k * 1024); } while (0)
; #define PG8_LDB(dst, b, h) do { _Pragma("unroll") for (int n = 0; n < 2; ++n) _Pragma("unroll") for (int k = 0; k < 2; ++k) dst[n][k] = *(const PG8_LAS bf16x8*)(lds + PG8_SB(b, h) + boff + n * 2048 + k * 1024); } while (0)
; #define PG8_MMA(ai, bj, At, Bt) do { __builtin_amdgcn_s_setprio(1); _Pragma("unroll") for (int m = 0; m < 4; ++m) _Pragma("unroll") for (int n = 0; n < 2; ++n) _Pragma("unroll") for (int k = 0; k < 2; ++k) \
;         acc[ai][bj][m][n] = __builtin_amdgcn_mfma_f32_16x16x32_bf16(Bt[n][k], At[m][k], acc[ai][bj][m][n], 0, 0, 0); __builtin_amdgcn_s_setprio(0); } while (0)
; #define PG8_WAIT_V(n) asm volatile("s_waitcnt vmcnt(" #n ")" ::: "memory")
; #define PG8_WAIT_L(n) asm volatile("s_waitcnt lgkmcnt(" #n ")" ::: "memory")
; #define PG8_BAR __builtin_amdgcn_s_barrier()
; #define PG8_SCHED __builtin_amdgcn_sched_barrier(0)
; template <class Epi, class Sched, bool ALIGN_EPI = false, bool SP2 = false>
; __device__ __forceinline__ void gemm_phase(PG8_LAS unsigned char* lds, const Gemm g, const Sched& S, const Epi& E, int tid_in) {
;     ...
;             const bool last = (t == nt - 2);
;             const char* a1 = cA + (size_t)(t + 1) * kstep;
;             const char* a2 = last ? nA : cA + (size_t)(t + 2) * kstep; const char* b2 = last ? nB : cB + (size_t)(t + 2) * kstep;
;             const char* a3 = a2 + kstep; const char* b3 = b2 + kstep;
;             if (last && has_next) S.a_ready(nxt);
;             if constexpr (SP2) {
;             PG8_LDB(B0, 0, 0); PG8_LDB(B1, 0, 1); PG8_SCHED; PG8_LDA(At, 0, 0); PG8_STAGE(PG8_SA(1, 1), a1 + hstep, voffA);
;             PG8_WAIT_V(8); PG8_WAIT_L(0); PG8_BAR; PG8_MMA(0, 0, At, B0); PG8_MMA(0, 1, At, B1); PG8_BAR; PG8_SCHED;
;             PG8_LDA(At, 0, 1); PG8_STAGE(PG8_SB(0, 0), b2, voffB); PG8_STAGE(PG8_SB(0, 1), b2 + hstep, voffB); PG8_STAGE(PG8_SA(0, 0), a2, voffA);
.LBB0_110:
	s_cmp_eq_u32 s11, 28
	s_cselect_b64 vcc, -1, 0
	s_add_i32 s13, 0, 0x10000
	s_add_i32 s14, 0, 0x14000
	v_lshl_add_u64 v[176:177], v[166:167], 0, s[52:53]
	v_add_u32_e32 v188, s13, v168
	v_add_u32_e32 v204, s14, v168
	v_cndmask_b32_e32 v241, v177, v131, vcc
	v_cndmask_b32_e32 v240, v176, v160, vcc
	ds_read_b128 v[176:179], v188
	ds_read_b128 v[180:183], v188 offset:1024
	ds_read_b128 v[184:187], v188 offset:2048
	ds_read_b128 v[188:191], v188 offset:3072
	ds_read_b128 v[192:195], v204
	ds_read_b128 v[196:199], v204 offset:1024
	ds_read_b128 v[200:203], v204 offset:2048
	ds_read_b128 v[204:207], v204 offset:3072
	v_cndmask_b32_e32 v243, v165, v161, vcc
	v_cndmask_b32_e32 v242, v164, v162, vcc
	v_lshl_add_u64 v[244:245], v[166:167], 0, v[154:155]
	s_add_i32 m0, s18, 0xc000
	ds_read_b128 v[208:211], v175
	ds_read_b128 v[212:215], v175 offset:1024
	ds_read_b128 v[216:219], v175 offset:2048
	ds_read_b128 v[220:223], v175 offset:3072
	ds_read_b128 v[224:227], v175 offset:4096
	ds_read_b128 v[228:231], v175 offset:5120
	ds_read_b128 v[232:235], v175 offset:6144
	ds_read_b128 v[236:239], v175 offset:7168
	global_load_lds_dwordx4 v[244:245], off
	v_lshl_add_u64 v[244:245], v[166:167], 0, v[152:153]
	s_add_i32 m0, s18, 0xe000
	s_nop 0
	global_load_lds_dwordx4 v[244:245], off
	s_waitcnt vmcnt(8) lgkmcnt(0)
	s_barrier
	s_setprio 1
	v_mfma_f32_16x16x32_bf16 v[124:127], v[176:179], v[208:211], v[124:127]
	v_mfma_f32_16x16x32_bf16 v[120:123], v[184:187], v[208:211], v[120:123]
	v_mfma_f32_16x16x32_bf16 v[116:119], v[176:179], v[216:219], v[116:119]
	v_mfma_f32_16x16x32_bf16 v[108:111], v[184:187], v[216:219], v[108:111]
	v_mfma_f32_16x16x32_bf16 v[100:103], v[176:179], v[224:227], v[100:103]
	v_mfma_f32_16x16x32_bf16 v[92:95], v[184:187], v[224:227], v[92:95]
	v_mfma_f32_16x16x32_bf16 v[84:87], v[176:179], v[232:235], v[84:87]
	v_mfma_f32_16x16x32_bf16 v[76:79], v[184:187], v[232:235], v[76:79]
	v_mfma_f32_16x16x32_bf16 v[124:127], v[180:183], v[212:215], v[124:127]
	v_mfma_f32_16x16x32_bf16 v[120:123], v[188:191], v[212:215], v[120:123]
	v_mfma_f32_16x16x32_bf16 v[116:119], v[180:183], v[220:223], v[116:119]
	v_mfma_f32_16x16x32_bf16 v[108:111], v[188:191], v[220:223], v[108:111]
	v_mfma_f32_16x16x32_bf16 v[100:103], v[180:183], v[228:231], v[100:103]
	v_mfma_f32_16x16x32_bf16 v[92:95], v[188:191], v[228:231], v[92:95]
	v_mfma_f32_16x16x32_bf16 v[84:87], v[180:183], v[236:239], v[84:87]
	v_mfma_f32_16x16x32_bf16 v[76:79], v[188:191], v[236:239], v[76:79]
	s_setprio 0
	s_setprio 1
	v_mfma_f32_16x16x32_bf16 v[112:115], v[192:195], v[208:211], v[112:115]
	v_mfma_f32_16x16x32_bf16 v[104:107], v[200:203], v[208:211], v[104:107]
	v_mfma_f32_16x16x32_bf16 v[96:99], v[192:195], v[216:219], v[96:99]
	v_mfma_f32_16x16x32_bf16 v[88:91], v[200:203], v[216:219], v[88:91]
	v_mfma_f32_16x16x32_bf16 v[80:83], v[192:195], v[224:227], v[80:83]
	v_mfma_f32_16x16x32_bf16 v[72:75], v[200:203], v[224:227], v[72:75]
	v_mfma_f32_16x16x32_bf16 v[68:71], v[192:195], v[232:235], v[68:71]
	v_mfma_f32_16x16x32_bf16 v[64:67], v[200:203], v[232:235], v[64:67]
	v_mfma_f32_16x16x32_bf16 v[112:115], v[196:199], v[212:215], v[112:115]
	v_mfma_f32_16x16x32_bf16 v[104:107], v[204:207], v[212:215], v[104:107]
	v_mfma_f32_16x16x32_bf16 v[96:99], v[196:199], v[220:223], v[96:99]
	v_mfma_f32_16x16x32_bf16 v[88:91], v[204:207], v[220:223], v[88:91]
	v_mfma_f32_16x16x32_bf16 v[80:83], v[196:199], v[228:231], v[80:83]
	v_mfma_f32_16x16x32_bf16 v[72:75], v[204:207], v[228:231], v[72:75]
	v_mfma_f32_16x16x32_bf16 v[68:71], v[196:199], v[236:239], v[68:71]
	v_mfma_f32_16x16x32_bf16 v[64:67], v[204:207], v[236:239], v[64:67]
	s_setprio 0
	s_barrier
	s_add_i32 s13, s13, s0
	v_lshl_add_u64 v[244:245], v[242:243], 0, v[128:129]
	s_mov_b32 m0, s13
	ds_read_b128 v[208:211], v175 offset:16384
	ds_read_b128 v[212:215], v175 offset:17408
	ds_read_b128 v[216:219], v175 offset:18432
	ds_read_b128 v[220:223], v175 offset:19456
	ds_read_b128 v[224:227], v175 offset:20480
	ds_read_b128 v[228:231], v175 offset:21504
	ds_read_b128 v[232:235], v175 offset:22528
	ds_read_b128 v[236:239], v175 offset:23552
	global_load_lds_dwordx4 v[244:245], off
	v_lshl_add_u64 v[246:247], v[242:243], 0, v[144:145]
	s_add_i32 m0, s13, 0x2000
	v_lshl_add_u64 v[248:249], v[242:243], 0, s[98:99]
	s_add_i32 s13, s14, s0
	global_load_lds_dwordx4 v[246:247], off
	v_lshl_add_u64 v[250:251], v[248:249], 0, v[128:129]
	s_mov_b32 m0, s13
	v_lshl_add_u64 v[248:249], v[248:249], 0, v[144:145]
	global_load_lds_dwordx4 v[250:251], off
	s_add_i32 m0, s13, 0x2000
	v_lshl_add_u64 v[250:251], v[240:241], 0, v[146:147]
	global_load_lds_dwordx4 v[248:249], off
	v_lshl_add_u64 v[248:249], v[240:241], 0, v[148:149]
	s_mov_b32 m0, s18
	s_nop 0
	global_load_lds_dwordx4 v[248:249], off
	s_mov_b32 m0, s19
	s_nop 0
	global_load_lds_dwordx4 v[250:251], off
	s_waitcnt vmcnt(8) lgkmcnt(0)
	s_barrier
; #define PG8_STAGE(bufoff, gbase, voff) do { _Pragma("unroll") for (int _i = 0; _i < 2; ++_i) \
;         __builtin_amdgcn_global_load_lds((const unsigned*)((const char*)(gbase) + (voff)[_i]), (PG8_LAS unsigned*)(lds + (bufoff) + ldsw + _i * 8192), 16, 0, 0); } while (0)
; #define PG8_LDA(dst, b, h) do { _Pragma("unroll") for (int m = 0; m < 4; ++m) _Pragma("unroll") for (int k = 0; k < 2; ++k) dst[m][k] = *(const PG8_LAS bf16x8*)(lds + PG8_SA(b, h) + aoff + m * 2048 + k * 1024); } while (0)
; #define PG8_LDB(dst, b, h) do { _Pragma("unroll") for (int n = 0; n < 2; ++n) _Pragma("unroll") for (int k = 0; k < 2; ++k) dst[n][k] = *(const PG8_LAS bf16x8*)(lds + PG8_SB(b, h) + boff + n * 2048 + k * 1024); } while (0)
; #define PG8_MMA(ai, bj, At, Bt) do { __builtin_amdgcn_s_setprio(1); _Pragma("unroll") for (int m = 0; m < 4; ++m) _Pragma("unroll") for (int n = 0; n < 2; ++n) _Pragma("unroll") for (int k = 0; k < 2; ++k) \
;         acc[ai][bj][m][n] = __builtin_amdgcn_mfma_f32_16x16x32_bf16(Bt[n][k], At[m][k], acc[ai][bj][m][n], 0, 0, 0); __builtin_amdgcn_s_setprio(0); } while (0)
; #define PG8_WAIT_V(n) asm volatile("s_waitcnt vmcnt(" #n ")" ::: "memory")
; #define PG8_WAIT_L(n) asm volatile("s_waitcnt lgkmcnt(" #n ")" ::: "memory")
; #define PG8_BAR __builtin_amdgcn_s_barrier()
; #define PG8_SCHED __builtin_amdgcn_sched_barrier(0)
; template <class Epi, class Sched, bool ALIGN_EPI = false, bool SP2 = false>
; __device__ __forceinline__ void gemm_phase(PG8_LAS unsigned char* lds, const Gemm g, const Sched& S, const Epi& E, int tid_in) {
;     ...
;             PG8_WAIT_V(8); PG8_WAIT_L(0); PG8_BAR; PG8_MMA(1, 0, At, B0); PG8_MMA(1, 1, At, B1); PG8_BAR; PG8_SCHED;
;             PG8_LDB(B0, 1, 0); PG8_LDB(B1, 1, 1); PG8_SCHED; PG8_LDA(At, 1, 0); PG8_STAGE(PG8_SA(0, 1), a2 + hstep, voffA);
;             PG8_WAIT_V(8); PG8_WAIT_L(0); PG8_BAR; PG8_MMA(0, 0, At, B0); PG8_MMA(0, 1, At, B1); PG8_BAR; PG8_SCHED;
	s_setprio 1
	v_mfma_f32_16x16x32_bf16 v[60:63], v[176:179], v[208:211], v[60:63]
	v_mfma_f32_16x16x32_bf16 v[56:59], v[184:187], v[208:211], v[56:59]
	v_mfma_f32_16x16x32_bf16 v[52:55], v[176:179], v[216:219], v[52:55]
	v_mfma_f32_16x16x32_bf16 v[44:47], v[184:187], v[216:219], v[44:47]
	v_mfma_f32_16x16x32_bf16 v[36:39], v[176:179], v[224:227], v[36:39]
	v_mfma_f32_16x16x32_bf16 v[28:31], v[184:187], v[224:227], v[28:31]
	v_mfma_f32_16x16x32_bf16 v[20:23], v[176:179], v[232:235], v[20:23]
	v_mfma_f32_16x16x32_bf16 v[12:15], v[184:187], v[232:235], v[12:15]
	v_mfma_f32_16x16x32_bf16 v[60:63], v[180:183], v[212:215], v[60:63]
	v_mfma_f32_16x16x32_bf16 v[56:59], v[188:191], v[212:215], v[56:59]
	v_mfma_f32_16x16x32_bf16 v[52:55], v[180:183], v[220:223], v[52:55]
	v_mfma_f32_16x16x32_bf16 v[44:47], v[188:191], v[220:223], v[44:47]
	v_mfma_f32_16x16x32_bf16 v[36:39], v[180:183], v[228:231], v[36:39]
	v_mfma_f32_16x16x32_bf16 v[28:31], v[188:191], v[228:231], v[28:31]
	v_mfma_f32_16x16x32_bf16 v[20:23], v[180:183], v[236:239], v[20:23]
	v_mfma_f32_16x16x32_bf16 v[12:15], v[188:191], v[236:239], v[12:15]
	s_setprio 0
	s_setprio 1
	v_mfma_f32_16x16x32_bf16 v[48:51], v[192:195], v[208:211], v[48:51]
	v_mfma_f32_16x16x32_bf16 v[40:43], v[200:203], v[208:211], v[40:43]
	v_mfma_f32_16x16x32_bf16 v[32:35], v[192:195], v[216:219], v[32:35]
	v_mfma_f32_16x16x32_bf16 v[24:27], v[200:203], v[216:219], v[24:27]
	v_mfma_f32_16x16x32_bf16 v[16:19], v[192:195], v[224:227], v[16:19]
	v_mfma_f32_16x16x32_bf16 v[8:11], v[200:203], v[224:227], v[8:11]
	v_mfma_f32_16x16x32_bf16 v[4:7], v[192:195], v[232:235], v[4:7]
	v_mfma_f32_16x16x32_bf16 v[0:3], v[200:203], v[232:235], v[0:3]
	v_mfma_f32_16x16x32_bf16 v[48:51], v[196:199], v[212:215], v[48:51]
	v_mfma_f32_16x16x32_bf16 v[40:43], v[204:207], v[212:215], v[40:43]
	v_mfma_f32_16x16x32_bf16 v[32:35], v[196:199], v[220:223], v[32:35]
	v_mfma_f32_16x16x32_bf16 v[24:27], v[204:207], v[220:223], v[24:27]
	v_mfma_f32_16x16x32_bf16 v[16:19], v[196:199], v[228:231], v[16:19]
	v_mfma_f32_16x16x32_bf16 v[8:11], v[204:207], v[228:231], v[8:11]
	v_mfma_f32_16x16x32_bf16 v[4:7], v[196:199], v[236:239], v[4:7]
	v_mfma_f32_16x16x32_bf16 v[0:3], v[204:207], v[236:239], v[0:3]
	s_setprio 0
	s_barrier
	s_add_i32 s13, 0, 0x18000
	s_add_i32 s14, 0, 0x1c000
	v_add_u32_e32 v188, s13, v168
	v_add_u32_e32 v204, s14, v168
	ds_read_b128 v[176:179], v188
	ds_read_b128 v[180:183], v188 offset:1024
	ds_read_b128 v[184:187], v188 offset:2048
	ds_read_b128 v[188:191], v188 offset:3072
	ds_read_b128 v[192:195], v204
	ds_read_b128 v[196:199], v204 offset:1024
	ds_read_b128 v[200:203], v204 offset:2048
	ds_read_b128 v[204:207], v204 offset:3072
	v_lshl_add_u64 v[240:241], v[240:241], 0, s[98:99]
	s_mov_b32 m0, s20
	v_lshl_add_u64 v[252:253], v[240:241], 0, v[148:149]
	ds_read_b128 v[208:211], v175 offset:32768
	ds_read_b128 v[212:215], v175 offset:33792
	ds_read_b128 v[216:219], v175 offset:34816
	ds_read_b128 v[220:223], v175 offset:35840
	ds_read_b128 v[224:227], v175 offset:36864
	ds_read_b128 v[228:231], v175 offset:37888
	ds_read_b128 v[232:235], v175 offset:38912
	ds_read_b128 v[236:239], v175 offset:39936
	global_load_lds_dwordx4 v[252:253], off
	v_lshl_add_u64 v[240:241], v[240:241], 0, v[146:147]
	s_mov_b32 m0, s21
	s_nop 0
	global_load_lds_dwordx4 v[240:241], off
	s_waitcnt vmcnt(8) lgkmcnt(0)
	s_barrier
	s_setprio 1
	v_mfma_f32_16x16x32_bf16 v[124:127], v[176:179], v[208:211], v[124:127]
	v_mfma_f32_16x16x32_bf16 v[120:123], v[184:187], v[208:211], v[120:123]
	v_mfma_f32_16x16x32_bf16 v[116:119], v[176:179], v[216:219], v[116:119]
	v_mfma_f32_16x16x32_bf16 v[108:111], v[184:187], v[216:219], v[108:111]
	v_mfma_f32_16x16x32_bf16 v[100:103], v[176:179], v[224:227], v[100:103]
	v_mfma_f32_16x16x32_bf16 v[92:95], v[184:187], v[224:227], v[92:95]
	v_mfma_f32_16x16x32_bf16 v[84:87], v[176:179], v[232:235], v[84:87]
	v_mfma_f32_16x16x32_bf16 v[76:79], v[184:187], v[232:235], v[76:79]
	v_mfma_f32_16x16x32_bf16 v[124:127], v[180:183], v[212:215], v[124:127]
	v_mfma_f32_16x16x32_bf16 v[120:123], v[188:191], v[212:215], v[120:123]
	v_mfma_f32_16x16x32_bf16 v[116:119], v[180:183], v[220:223], v[116:119]
	v_mfma_f32_16x16x32_bf16 v[108:111], v[188:191], v[220:223], v[108:111]
	v_mfma_f32_16x16x32_bf16 v[100:103], v[180:183], v[228:231], v[100:103]
	v_mfma_f32_16x16x32_bf16 v[92:95], v[188:191], v[228:231], v[92:95]
	v_mfma_f32_16x16x32_bf16 v[84:87], v[180:183], v[236:239], v[84:87]
	v_mfma_f32_16x16x32_bf16 v[76:79], v[188:191], v[236:239], v[76:79]
	s_setprio 0
	s_setprio 1
	v_mfma_f32_16x16x32_bf16 v[112:115], v[192:195], v[208:211], v[112:115]
	v_mfma_f32_16x16x32_bf16 v[104:107], v[200:203], v[208:211], v[104:107]
	v_mfma_f32_16x16x32_bf16 v[96:99], v[192:195], v[216:219], v[96:99]
	v_mfma_f32_16x16x32_bf16 v[88:91], v[200:203], v[216:219], v[88:91]
	v_mfma_f32_16x16x32_bf16 v[80:83], v[192:195], v[224:227], v[80:83]
	v_mfma_f32_16x16x32_bf16 v[72:75], v[200:203], v[224:227], v[72:75]
	v_mfma_f32_16x16x32_bf16 v[68:71], v[192:195], v[232:235], v[68:71]
	v_mfma_f32_16x16x32_bf16 v[64:67], v[200:203], v[232:235], v[64:67]
	v_mfma_f32_16x16x32_bf16 v[112:115], v[196:199], v[212:215], v[112:115]
	v_mfma_f32_16x16x32_bf16 v[104:107], v[204:207], v[212:215], v[104:107]
	v_mfma_f32_16x16x32_bf16 v[96:99], v[196:199], v[220:223], v[96:99]
	v_mfma_f32_16x16x32_bf16 v[88:91], v[204:207], v[220:223], v[88:91]
	v_mfma_f32_16x16x32_bf16 v[80:83], v[196:199], v[228:231], v[80:83]
	v_mfma_f32_16x16x32_bf16 v[72:75], v[204:207], v[228:231], v[72:75]
	v_mfma_f32_16x16x32_bf16 v[68:71], v[196:199], v[236:239], v[68:71]
	v_mfma_f32_16x16x32_bf16 v[64:67], v[204:207], v[236:239], v[64:67]
	s_setprio 0
	s_barrier
; #define PG8_STAGE(bufoff, gbase, voff) do { _Pragma("unroll") for (int _i = 0; _i < 2; ++_i) \
;         __builtin_amdgcn_global_load_lds((const unsigned*)((const char*)(gbase) + (voff)[_i]), (PG8_LAS unsigned*)(lds + (bufoff) + ldsw + _i * 8192), 16, 0, 0); } while (0)
; #define PG8_LDA(dst, b, h) do { _Pragma("unroll") for (int m = 0; m < 4; ++m) _Pragma("unroll") for (int k = 0; k < 2; ++k) dst[m][k] = *(const PG8_LAS bf16x8*)(lds + PG8_SA(b, h) + aoff + m * 2048 + k * 1024); } while (0)
; #define PG8_MMA(ai, bj, At, Bt) do { __builtin_amdgcn_s_setprio(1); _Pragma("unroll") for (int m = 0; m < 4; ++m) _Pragma("unroll") for (int n = 0; n < 2; ++n) _Pragma("unroll") for (int k = 0; k < 2; ++k) \
;         acc[ai][bj][m][n] = __builtin_amdgcn_mfma_f32_16x16x32_bf16(Bt[n][k], At[m][k], acc[ai][bj][m][n], 0, 0, 0); __builtin_amdgcn_s_setprio(0); } while (0)
; #define PG8_WAIT_V(n) asm volatile("s_waitcnt vmcnt(" #n ")" ::: "memory")
; #define PG8_WAIT_L(n) asm volatile("s_waitcnt lgkmcnt(" #n ")" ::: "memory")
; #define PG8_BAR __builtin_amdgcn_s_barrier()
; #define PG8_SCHED __builtin_amdgcn_sched_barrier(0)
; template <class Epi, class Sched, bool ALIGN_EPI = false, bool SP2 = false>
; __device__ __forceinline__ void gemm_phase(PG8_LAS unsigned char* lds, const Gemm g, const Sched& S, const Epi& E, int tid_in) {
;     ...
;         for (int t = 0; t < nt; t += 2) {
;             const bool last = (t == nt - 2);
;             const char* a1 = cA + (size_t)(t + 1) * kstep;
;             const char* a2 = last ? nA : cA + (size_t)(t + 2) * kstep; const char* b2 = last ? nB : cB + (size_t)(t + 2) * kstep;
;             const char* a3 = a2 + kstep; const char* b3 = b2 + kstep;
;     ...
;             PG8_LDA(At, 1, 1); PG8_STAGE(PG8_SB(1, 0), b3, voffB); PG8_STAGE(PG8_SB(1, 1), b3 + hstep, voffB); PG8_STAGE(PG8_SA(1, 0), a3, voffA);
;             PG8_WAIT_V(8); PG8_WAIT_L(0); PG8_BAR; PG8_MMA(1, 0, At, B0); PG8_MMA(1, 1, At, B1); PG8_BAR; PG8_SCHED;
;     ...
;         if constexpr (ALIGN_EPI) { if (wr == 0) PG8_BAR; }
	s_add_i32 s13, s13, s0
	v_lshl_add_u64 v[240:241], v[244:245], 0, s[70:71]
	s_mov_b32 m0, s13
	ds_read_b128 v[208:211], v175 offset:49152
	ds_read_b128 v[212:215], v175 offset:50176
	ds_read_b128 v[216:219], v175 offset:51200
	ds_read_b128 v[220:223], v175 offset:52224
	ds_read_b128 v[224:227], v175 offset:53248
	ds_read_b128 v[228:231], v175 offset:54272
	ds_read_b128 v[232:235], v175 offset:55296
	ds_read_b128 v[236:239], v175 offset:56320
	global_load_lds_dwordx4 v[240:241], off
	v_lshl_add_u64 v[240:241], v[246:247], 0, s[70:71]
	s_add_i32 m0, s13, 0x2000
	s_add_i32 s13, s14, s0
	global_load_lds_dwordx4 v[240:241], off
	v_lshl_add_u64 v[240:241], v[242:243], 0, s[86:87]
	v_lshl_add_u64 v[242:243], v[240:241], 0, v[128:129]
	s_mov_b32 m0, s13
	v_lshl_add_u64 v[240:241], v[240:241], 0, v[144:145]
	global_load_lds_dwordx4 v[242:243], off
	s_add_i32 m0, s13, 0x2000
	s_nop 0
	global_load_lds_dwordx4 v[240:241], off
	v_lshl_add_u64 v[240:241], v[248:249], 0, s[70:71]
	s_mov_b32 m0, s22
	s_nop 0
	global_load_lds_dwordx4 v[240:241], off
	v_lshl_add_u64 v[240:241], v[250:251], 0, s[70:71]
	s_mov_b32 m0, s23
	s_nop 0
	global_load_lds_dwordx4 v[240:241], off
	s_waitcnt vmcnt(8) lgkmcnt(0)
	s_barrier
	s_setprio 1
	v_mfma_f32_16x16x32_bf16 v[60:63], v[176:179], v[208:211], v[60:63]
	v_mfma_f32_16x16x32_bf16 v[56:59], v[184:187], v[208:211], v[56:59]
	v_mfma_f32_16x16x32_bf16 v[52:55], v[176:179], v[216:219], v[52:55]
	v_mfma_f32_16x16x32_bf16 v[44:47], v[184:187], v[216:219], v[44:47]
	v_mfma_f32_16x16x32_bf16 v[36:39], v[176:179], v[224:227], v[36:39]
	v_mfma_f32_16x16x32_bf16 v[28:31], v[184:187], v[224:227], v[28:31]
	v_mfma_f32_16x16x32_bf16 v[20:23], v[176:179], v[232:235], v[20:23]
	v_mfma_f32_16x16x32_bf16 v[12:15], v[184:187], v[232:235], v[12:15]
	v_mfma_f32_16x16x32_bf16 v[60:63], v[180:183], v[212:215], v[60:63]
	v_mfma_f32_16x16x32_bf16 v[56:59], v[188:191], v[212:215], v[56:59]
	v_mfma_f32_16x16x32_bf16 v[52:55], v[180:183], v[220:223], v[52:55]
	v_mfma_f32_16x16x32_bf16 v[44:47], v[188:191], v[220:223], v[44:47]
	v_mfma_f32_16x16x32_bf16 v[36:39], v[180:183], v[228:231], v[36:39]
	v_mfma_f32_16x16x32_bf16 v[28:31], v[188:191], v[228:231], v[28:31]
	v_mfma_f32_16x16x32_bf16 v[20:23], v[180:183], v[236:239], v[20:23]
	v_mfma_f32_16x16x32_bf16 v[12:15], v[188:191], v[236:239], v[12:15]
	s_setprio 0
	s_setprio 1
	v_mfma_f32_16x16x32_bf16 v[48:51], v[192:195], v[208:211], v[48:51]
	v_mfma_f32_16x16x32_bf16 v[40:43], v[200:203], v[208:211], v[40:43]
	v_mfma_f32_16x16x32_bf16 v[32:35], v[192:195], v[216:219], v[32:35]
	v_mfma_f32_16x16x32_bf16 v[24:27], v[200:203], v[216:219], v[24:27]
	v_mfma_f32_16x16x32_bf16 v[16:19], v[192:195], v[224:227], v[16:19]
	v_mfma_f32_16x16x32_bf16 v[8:11], v[200:203], v[224:227], v[8:11]
	v_mfma_f32_16x16x32_bf16 v[4:7], v[192:195], v[232:235], v[4:7]
	v_mfma_f32_16x16x32_bf16 v[0:3], v[200:203], v[232:235], v[0:3]
	v_mfma_f32_16x16x32_bf16 v[48:51], v[196:199], v[212:215], v[48:51]
	v_mfma_f32_16x16x32_bf16 v[40:43], v[204:207], v[212:215], v[40:43]
	v_mfma_f32_16x16x32_bf16 v[32:35], v[196:199], v[220:223], v[32:35]
	v_mfma_f32_16x16x32_bf16 v[24:27], v[204:207], v[220:223], v[24:27]
	v_mfma_f32_16x16x32_bf16 v[16:19], v[196:199], v[228:231], v[16:19]
	v_mfma_f32_16x16x32_bf16 v[8:11], v[204:207], v[228:231], v[8:11]
	v_mfma_f32_16x16x32_bf16 v[4:7], v[196:199], v[236:239], v[4:7]
	v_mfma_f32_16x16x32_bf16 v[0:3], v[204:207], v[236:239], v[0:3]
	s_setprio 0
	s_barrier
	s_add_i32 s11, s11, 2
	v_lshl_add_u64 v[164:165], v[164:165], 0, s[82:83]
	s_cmp_gt_u32 s11, 29
	v_lshl_add_u64 v[166:167], v[166:167], 0, s[82:83]
	s_cbranch_scc0 .LBB0_110
	s_and_b64 vcc, exec, s[8:9]
	s_cbranch_vccz .LBB0_113
	s_barrier

; #define PG8_STAGE(bufoff, gbase, voff) do { _Pragma("unroll") for (int _i = 0; _i < 2; ++_i) \
;         __builtin_amdgcn_global_load_lds((const unsigned*)((const char*)(gbase) + (voff)[_i]), (PG8_LAS unsigned*)(lds + (bufoff) + ldsw + _i * 8192), 16, 0, 0); } while (0)
; #define PG8_LDA(dst, b, h) do { _Pragma("unroll") for (int m = 0; m < 4; ++m) _Pragma("unroll") for (int k = 0; k < 2; ++k) dst[m][k] = *(const PG8_LAS bf16x8*)(lds + PG8_SA(b, h) + aoff + m * 2048 + k * 1024); } while (0)
; #define PG8_LDB(dst, b, h) do { _Pragma("unroll") for (int n = 0; n < 2; ++n) _Pragma("unroll") for (int k = 0; k < 2; ++k) dst[n][k] = *(const PG8_LAS bf16x8*)(lds + PG8_SB(b, h) + boff + n * 2048 + k * 1024); } while (0)
; #define PG8_MMA(ai, bj, At, Bt) do { __builtin_amdgcn_s_setprio(1); _Pragma("unroll") for (int m = 0; m < 4; ++m) _Pragma("unroll") for (int n = 0; n < 2; ++n) _Pragma("unroll") for (int k = 0; k < 2; ++k) \
;         acc[ai][bj][m][n] = __builtin_amdgcn_mfma_f32_16x16x32_bf16(Bt[n][k], At[m][k], acc[ai][bj][m][n], 0, 0, 0); __builtin_amdgcn_s_setprio(0); } while (0)
; #define PG8_WAIT_V(n) asm volatile("s_waitcnt vmcnt(" #n ")" ::: "memory")
; #define PG8_WAIT_L(n) asm volatile("s_waitcnt lgkmcnt(" #n ")" ::: "memory")
; #define PG8_BAR __builtin_amdgcn_s_barrier()
; #define PG8_SCHED __builtin_amdgcn_sched_barrier(0)
; template <class Epi, class Sched, bool ALIGN_EPI = false, bool SP2 = false>
; __device__ __forceinline__ void gemm_phase(PG8_LAS unsigned char* lds, const Gemm g, const Sched& S, const Epi& E, int tid_in) {
;     ...
;             const bool last = (t == nt - 2);
;             const char* a1 = cA + (size_t)(t + 1) * kstep;
;             const char* a2 = last ? nA : cA + (size_t)(t + 2) * kstep; const char* b2 = last ? nB : cB + (size_t)(t + 2) * kstep;
;             const char* a3 = a2 + kstep; const char* b3 = b2 + kstep;
;             if (last && has_next) S.a_ready(nxt);
;             if constexpr (SP2) {
;             PG8_LDB(B0, 0, 0); PG8_LDB(B1, 0, 1); PG8_SCHED; PG8_LDA(At, 0, 0); PG8_STAGE(PG8_SA(1, 1), a1 + hstep, voffA);
;             PG8_WAIT_V(8); PG8_WAIT_L(0); PG8_BAR; PG8_MMA(0, 0, At, B0); PG8_MMA(0, 1, At, B1); PG8_BAR; PG8_SCHED;
;             PG8_LDA(At, 0, 1); PG8_STAGE(PG8_SB(0, 0), b2, voffB); PG8_STAGE(PG8_SB(0, 1), b2 + hstep, voffB); PG8_STAGE(PG8_SA(0, 0), a2, voffA);
.LBB0_405:
	s_cmp_eq_u32 s2, 28
	s_cselect_b64 vcc, -1, 0
	s_add_i32 s3, 0, 0x10000
	s_add_i32 s13, 0, 0x14000
	v_lshl_add_u64 v[176:177], v[166:167], 0, s[52:53]
	v_add_u32_e32 v188, s3, v168
	v_add_u32_e32 v204, s13, v168
	v_cndmask_b32_e32 v241, v177, v131, vcc
	v_cndmask_b32_e32 v240, v176, v160, vcc
	ds_read_b128 v[176:179], v188
	ds_read_b128 v[180:183], v188 offset:1024
	ds_read_b128 v[184:187], v188 offset:2048
	ds_read_b128 v[188:191], v188 offset:3072
	ds_read_b128 v[192:195], v204
	ds_read_b128 v[196:199], v204 offset:1024
	ds_read_b128 v[200:203], v204 offset:2048
	ds_read_b128 v[204:207], v204 offset:3072
	v_cndmask_b32_e32 v243, v165, v161, vcc
	v_cndmask_b32_e32 v242, v164, v162, vcc
	v_lshl_add_u64 v[244:245], v[166:167], 0, v[154:155]
	s_add_i32 m0, s16, 0xc000
	ds_read_b128 v[208:211], v175
	ds_read_b128 v[212:215], v175 offset:1024
	ds_read_b128 v[216:219], v175 offset:2048
	ds_read_b128 v[220:223], v175 offset:3072
	ds_read_b128 v[224:227], v175 offset:4096
	ds_read_b128 v[228:231], v175 offset:5120
	ds_read_b128 v[232:235], v175 offset:6144
	ds_read_b128 v[236:239], v175 offset:7168
	global_load_lds_dwordx4 v[244:245], off
	v_lshl_add_u64 v[244:245], v[166:167], 0, v[152:153]
	s_add_i32 m0, s16, 0xe000
	s_nop 0
	global_load_lds_dwordx4 v[244:245], off
	s_waitcnt vmcnt(8) lgkmcnt(0)
	s_barrier
	s_setprio 1
	v_mfma_f32_16x16x32_bf16 v[124:127], v[176:179], v[208:211], v[124:127]
	v_mfma_f32_16x16x32_bf16 v[120:123], v[184:187], v[208:211], v[120:123]
	v_mfma_f32_16x16x32_bf16 v[116:119], v[176:179], v[216:219], v[116:119]
	v_mfma_f32_16x16x32_bf16 v[108:111], v[184:187], v[216:219], v[108:111]
	v_mfma_f32_16x16x32_bf16 v[100:103], v[176:179], v[224:227], v[100:103]
	v_mfma_f32_16x16x32_bf16 v[92:95], v[184:187], v[224:227], v[92:95]
	v_mfma_f32_16x16x32_bf16 v[84:87], v[176:179], v[232:235], v[84:87]
	v_mfma_f32_16x16x32_bf16 v[76:79], v[184:187], v[232:235], v[76:79]
	v_mfma_f32_16x16x32_bf16 v[124:127], v[180:183], v[212:215], v[124:127]
	v_mfma_f32_16x16x32_bf16 v[120:123], v[188:191], v[212:215], v[120:123]
	v_mfma_f32_16x16x32_bf16 v[116:119], v[180:183], v[220:223], v[116:119]
	v_mfma_f32_16x16x32_bf16 v[108:111], v[188:191], v[220:223], v[108:111]
	v_mfma_f32_16x16x32_bf16 v[100:103], v[180:183], v[228:231], v[100:103]
	v_mfma_f32_16x16x32_bf16 v[92:95], v[188:191], v[228:231], v[92:95]
	v_mfma_f32_16x16x32_bf16 v[84:87], v[180:183], v[236:239], v[84:87]
	v_mfma_f32_16x16x32_bf16 v[76:79], v[188:191], v[236:239], v[76:79]
	s_setprio 0
	s_setprio 1
	v_mfma_f32_16x16x32_bf16 v[112:115], v[192:195], v[208:211], v[112:115]
	v_mfma_f32_16x16x32_bf16 v[104:107], v[200:203], v[208:211], v[104:107]
	v_mfma_f32_16x16x32_bf16 v[96:99], v[192:195], v[216:219], v[96:99]
	v_mfma_f32_16x16x32_bf16 v[88:91], v[200:203], v[216:219], v[88:91]
	v_mfma_f32_16x16x32_bf16 v[80:83], v[192:195], v[224:227], v[80:83]
	v_mfma_f32_16x16x32_bf16 v[72:75], v[200:203], v[224:227], v[72:75]
	v_mfma_f32_16x16x32_bf16 v[68:71], v[192:195], v[232:235], v[68:71]
	v_mfma_f32_16x16x32_bf16 v[64:67], v[200:203], v[232:235], v[64:67]
	v_mfma_f32_16x16x32_bf16 v[112:115], v[196:199], v[212:215], v[112:115]
	v_mfma_f32_16x16x32_bf16 v[104:107], v[204:207], v[212:215], v[104:107]
	v_mfma_f32_16x16x32_bf16 v[96:99], v[196:199], v[220:223], v[96:99]
	v_mfma_f32_16x16x32_bf16 v[88:91], v[204:207], v[220:223], v[88:91]
	v_mfma_f32_16x16x32_bf16 v[80:83], v[196:199], v[228:231], v[80:83]
	v_mfma_f32_16x16x32_bf16 v[72:75], v[204:207], v[228:231], v[72:75]
	v_mfma_f32_16x16x32_bf16 v[68:71], v[196:199], v[236:239], v[68:71]
	v_mfma_f32_16x16x32_bf16 v[64:67], v[204:207], v[236:239], v[64:67]
	s_setprio 0
	s_barrier
	s_add_i32 s3, s3, s1
	v_lshl_add_u64 v[244:245], v[242:243], 0, v[128:129]
	s_mov_b32 m0, s3
	ds_read_b128 v[208:211], v175 offset:16384
	ds_read_b128 v[212:215], v175 offset:17408
	ds_read_b128 v[216:219], v175 offset:18432
	ds_read_b128 v[220:223], v175 offset:19456
	ds_read_b128 v[224:227], v175 offset:20480
	ds_read_b128 v[228:231], v175 offset:21504
	ds_read_b128 v[232:235], v175 offset:22528
	ds_read_b128 v[236:239], v175 offset:23552
	global_load_lds_dwordx4 v[244:245], off
	v_lshl_add_u64 v[246:247], v[242:243], 0, v[144:145]
	s_add_i32 m0, s3, 0x2000
	v_lshl_add_u64 v[248:249], v[242:243], 0, s[98:99]
	s_add_i32 s3, s13, s1
	global_load_lds_dwordx4 v[246:247], off
	v_lshl_add_u64 v[250:251], v[248:249], 0, v[128:129]
	s_mov_b32 m0, s3
	v_lshl_add_u64 v[248:249], v[248:249], 0, v[144:145]
	global_load_lds_dwordx4 v[250:251], off
	s_add_i32 m0, s3, 0x2000
	v_lshl_add_u64 v[250:251], v[240:241], 0, v[146:147]
	global_load_lds_dwordx4 v[248:249], off
	v_lshl_add_u64 v[248:249], v[240:241], 0, v[148:149]
	s_mov_b32 m0, s16
	s_nop 0
	global_load_lds_dwordx4 v[248:249], off
	s_mov_b32 m0, s17
	s_nop 0
	global_load_lds_dwordx4 v[250:251], off
	s_waitcnt vmcnt(8) lgkmcnt(0)
	s_barrier
; #define PG8_STAGE(bufoff, gbase, voff) do { _Pragma("unroll") for (int _i = 0; _i < 2; ++_i) \
;         __builtin_amdgcn_global_load_lds((const unsigned*)((const char*)(gbase) + (voff)[_i]), (PG8_LAS unsigned*)(lds + (bufoff) + ldsw + _i * 8192), 16, 0, 0); } while (0)
; #define PG8_LDA(dst, b, h) do { _Pragma("unroll") for (int m = 0; m < 4; ++m) _Pragma("unroll") for (int k = 0; k < 2; ++k) dst[m][k] = *(const PG8_LAS bf16x8*)(lds + PG8_SA(b, h) + aoff + m * 2048 + k * 1024); } while (0)
; #define PG8_LDB(dst, b, h) do { _Pragma("unroll") for (int n = 0; n < 2; ++n) _Pragma("unroll") for (int k = 0; k < 2; ++k) dst[n][k] = *(const PG8_LAS bf16x8*)(lds + PG8_SB(b, h) + boff + n * 2048 + k * 1024); } while (0)
; #define PG8_MMA(ai, bj, At, Bt) do { __builtin_amdgcn_s_setprio(1); _Pragma("unroll") for (int m = 0; m < 4; ++m) _Pragma("unroll") for (int n = 0; n < 2; ++n) _Pragma("unroll") for (int k = 0; k < 2; ++k) \
;         acc[ai][bj][m][n] = __builtin_amdgcn_mfma_f32_16x16x32_bf16(Bt[n][k], At[m][k], acc[ai][bj][m][n], 0, 0, 0); __builtin_amdgcn_s_setprio(0); } while (0)
; #define PG8_WAIT_V(n) asm volatile("s_waitcnt vmcnt(" #n ")" ::: "memory")
; #define PG8_WAIT_L(n) asm volatile("s_waitcnt lgkmcnt(" #n ")" ::: "memory")
; #define PG8_BAR __builtin_amdgcn_s_barrier()
; #define PG8_SCHED __builtin_amdgcn_sched_barrier(0)
; template <class Epi, class Sched, bool ALIGN_EPI = false, bool SP2 = false>
; __device__ __forceinline__ void gemm_phase(PG8_LAS unsigned char* lds, const Gemm g, const Sched& S, const Epi& E, int tid_in) {
;     ...
;             PG8_WAIT_V(8); PG8_WAIT_L(0); PG8_BAR; PG8_MMA(1, 0, At, B0); PG8_MMA(1, 1, At, B1); PG8_BAR; PG8_SCHED;
;             PG8_LDB(B0, 1, 0); PG8_LDB(B1, 1, 1); PG8_SCHED; PG8_LDA(At, 1, 0); PG8_STAGE(PG8_SA(0, 1), a2 + hstep, voffA);
;             PG8_WAIT_V(8); PG8_WAIT_L(0); PG8_BAR; PG8_MMA(0, 0, At, B0); PG8_MMA(0, 1, At, B1); PG8_BAR; PG8_SCHED;
	s_setprio 1
	v_mfma_f32_16x16x32_bf16 v[60:63], v[176:179], v[208:211], v[60:63]
	v_mfma_f32_16x16x32_bf16 v[56:59], v[184:187], v[208:211], v[56:59]
	v_mfma_f32_16x16x32_bf16 v[52:55], v[176:179], v[216:219], v[52:55]
	v_mfma_f32_16x16x32_bf16 v[44:47], v[184:187], v[216:219], v[44:47]
	v_mfma_f32_16x16x32_bf16 v[36:39], v[176:179], v[224:227], v[36:39]
	v_mfma_f32_16x16x32_bf16 v[28:31], v[184:187], v[224:227], v[28:31]
	v_mfma_f32_16x16x32_bf16 v[20:23], v[176:179], v[232:235], v[20:23]
	v_mfma_f32_16x16x32_bf16 v[12:15], v[184:187], v[232:235], v[12:15]
	v_mfma_f32_16x16x32_bf16 v[60:63], v[180:183], v[212:215], v[60:63]
	v_mfma_f32_16x16x32_bf16 v[56:59], v[188:191], v[212:215], v[56:59]
	v_mfma_f32_16x16x32_bf16 v[52:55], v[180:183], v[220:223], v[52:55]
	v_mfma_f32_16x16x32_bf16 v[44:47], v[188:191], v[220:223], v[44:47]
	v_mfma_f32_16x16x32_bf16 v[36:39], v[180:183], v[228:231], v[36:39]
	v_mfma_f32_16x16x32_bf16 v[28:31], v[188:191], v[228:231], v[28:31]
	v_mfma_f32_16x16x32_bf16 v[20:23], v[180:183], v[236:239], v[20:23]
	v_mfma_f32_16x16x32_bf16 v[12:15], v[188:191], v[236:239], v[12:15]
	s_setprio 0
	s_setprio 1
	v_mfma_f32_16x16x32_bf16 v[48:51], v[192:195], v[208:211], v[48:51]
	v_mfma_f32_16x16x32_bf16 v[40:43], v[200:203], v[208:211], v[40:43]
	v_mfma_f32_16x16x32_bf16 v[32:35], v[192:195], v[216:219], v[32:35]
	v_mfma_f32_16x16x32_bf16 v[24:27], v[200:203], v[216:219], v[24:27]
	v_mfma_f32_16x16x32_bf16 v[16:19], v[192:195], v[224:227], v[16:19]
	v_mfma_f32_16x16x32_bf16 v[8:11], v[200:203], v[224:227], v[8:11]
	v_mfma_f32_16x16x32_bf16 v[4:7], v[192:195], v[232:235], v[4:7]
	v_mfma_f32_16x16x32_bf16 v[0:3], v[200:203], v[232:235], v[0:3]
	v_mfma_f32_16x16x32_bf16 v[48:51], v[196:199], v[212:215], v[48:51]
	v_mfma_f32_16x16x32_bf16 v[40:43], v[204:207], v[212:215], v[40:43]
	v_mfma_f32_16x16x32_bf16 v[32:35], v[196:199], v[220:223], v[32:35]
	v_mfma_f32_16x16x32_bf16 v[24:27], v[204:207], v[220:223], v[24:27]
	v_mfma_f32_16x16x32_bf16 v[16:19], v[196:199], v[228:231], v[16:19]
	v_mfma_f32_16x16x32_bf16 v[8:11], v[204:207], v[228:231], v[8:11]
	v_mfma_f32_16x16x32_bf16 v[4:7], v[196:199], v[236:239], v[4:7]
	v_mfma_f32_16x16x32_bf16 v[0:3], v[204:207], v[236:239], v[0:3]
	s_setprio 0
	s_barrier
	s_add_i32 s3, 0, 0x18000
	s_add_i32 s13, 0, 0x1c000
	v_add_u32_e32 v188, s3, v168
	v_add_u32_e32 v204, s13, v168
	ds_read_b128 v[176:179], v188
	ds_read_b128 v[180:183], v188 offset:1024
	ds_read_b128 v[184:187], v188 offset:2048
	ds_read_b128 v[188:191], v188 offset:3072
	ds_read_b128 v[192:195], v204
	ds_read_b128 v[196:199], v204 offset:1024
	ds_read_b128 v[200:203], v204 offset:2048
	ds_read_b128 v[204:207], v204 offset:3072
	v_lshl_add_u64 v[240:241], v[240:241], 0, s[98:99]
	s_mov_b32 m0, s18
	v_lshl_add_u64 v[252:253], v[240:241], 0, v[148:149]
	ds_read_b128 v[208:211], v175 offset:32768
	ds_read_b128 v[212:215], v175 offset:33792
	ds_read_b128 v[216:219], v175 offset:34816
	ds_read_b128 v[220:223], v175 offset:35840
	ds_read_b128 v[224:227], v175 offset:36864
	ds_read_b128 v[228:231], v175 offset:37888
	ds_read_b128 v[232:235], v175 offset:38912
	ds_read_b128 v[236:239], v175 offset:39936
	global_load_lds_dwordx4 v[252:253], off
	v_lshl_add_u64 v[240:241], v[240:241], 0, v[146:147]
	s_mov_b32 m0, s19
	s_nop 0
	global_load_lds_dwordx4 v[240:241], off
	s_waitcnt vmcnt(8) lgkmcnt(0)
	s_barrier
	s_setprio 1
	v_mfma_f32_16x16x32_bf16 v[124:127], v[176:179], v[208:211], v[124:127]
	v_mfma_f32_16x16x32_bf16 v[120:123], v[184:187], v[208:211], v[120:123]
	v_mfma_f32_16x16x32_bf16 v[116:119], v[176:179], v[216:219], v[116:119]
	v_mfma_f32_16x16x32_bf16 v[108:111], v[184:187], v[216:219], v[108:111]
	v_mfma_f32_16x16x32_bf16 v[100:103], v[176:179], v[224:227], v[100:103]
	v_mfma_f32_16x16x32_bf16 v[92:95], v[184:187], v[224:227], v[92:95]
	v_mfma_f32_16x16x32_bf16 v[84:87], v[176:179], v[232:235], v[84:87]
	v_mfma_f32_16x16x32_bf16 v[76:79], v[184:187], v[232:235], v[76:79]
	v_mfma_f32_16x16x32_bf16 v[124:127], v[180:183], v[212:215], v[124:127]
	v_mfma_f32_16x16x32_bf16 v[120:123], v[188:191], v[212:215], v[120:123]
	v_mfma_f32_16x16x32_bf16 v[116:119], v[180:183], v[220:223], v[116:119]
	v_mfma_f32_16x16x32_bf16 v[108:111], v[188:191], v[220:223], v[108:111]
	v_mfma_f32_16x16x32_bf16 v[100:103], v[180:183], v[228:231], v[100:103]
	v_mfma_f32_16x16x32_bf16 v[92:95], v[188:191], v[228:231], v[92:95]
	v_mfma_f32_16x16x32_bf16 v[84:87], v[180:183], v[236:239], v[84:87]
	v_mfma_f32_16x16x32_bf16 v[76:79], v[188:191], v[236:239], v[76:79]
	s_setprio 0
	s_setprio 1
	v_mfma_f32_16x16x32_bf16 v[112:115], v[192:195], v[208:211], v[112:115]
	v_mfma_f32_16x16x32_bf16 v[104:107], v[200:203], v[208:211], v[104:107]
	v_mfma_f32_16x16x32_bf16 v[96:99], v[192:195], v[216:219], v[96:99]
	v_mfma_f32_16x16x32_bf16 v[88:91], v[200:203], v[216:219], v[88:91]
	v_mfma_f32_16x16x32_bf16 v[80:83], v[192:195], v[224:227], v[80:83]
	v_mfma_f32_16x16x32_bf16 v[72:75], v[200:203], v[224:227], v[72:75]
	v_mfma_f32_16x16x32_bf16 v[68:71], v[192:195], v[232:235], v[68:71]
	v_mfma_f32_16x16x32_bf16 v[64:67], v[200:203], v[232:235], v[64:67]
	v_mfma_f32_16x16x32_bf16 v[112:115], v[196:199], v[212:215], v[112:115]
	v_mfma_f32_16x16x32_bf16 v[104:107], v[204:207], v[212:215], v[104:107]
	v_mfma_f32_16x16x32_bf16 v[96:99], v[196:199], v[220:223], v[96:99]
	v_mfma_f32_16x16x32_bf16 v[88:91], v[204:207], v[220:223], v[88:91]
	v_mfma_f32_16x16x32_bf16 v[80:83], v[196:199], v[228:231], v[80:83]
	v_mfma_f32_16x16x32_bf16 v[72:75], v[204:207], v[228:231], v[72:75]
	v_mfma_f32_16x16x32_bf16 v[68:71], v[196:199], v[236:239], v[68:71]
	v_mfma_f32_16x16x32_bf16 v[64:67], v[204:207], v[236:239], v[64:67]
	s_setprio 0
	s_barrier
; #define PG8_STAGE(bufoff, gbase, voff) do { _Pragma("unroll") for (int _i = 0; _i < 2; ++_i) \
;         __builtin_amdgcn_global_load_lds((const unsigned*)((const char*)(gbase) + (voff)[_i]), (PG8_LAS unsigned*)(lds + (bufoff) + ldsw + _i * 8192), 16, 0, 0); } while (0)
; #define PG8_LDA(dst, b, h) do { _Pragma("unroll") for (int m = 0; m < 4; ++m) _Pragma("unroll") for (int k = 0; k < 2; ++k) dst[m][k] = *(const PG8_LAS bf16x8*)(lds + PG8_SA(b, h) + aoff + m * 2048 + k * 1024); } while (0)
; #define PG8_MMA(ai, bj, At, Bt) do { __builtin_amdgcn_s_setprio(1); _Pragma("unroll") for (int m = 0; m < 4; ++m) _Pragma("unroll") for (int n = 0; n < 2; ++n) _Pragma("unroll") for (int k = 0; k < 2; ++k) \
;         acc[ai][bj][m][n] = __builtin_amdgcn_mfma_f32_16x16x32_bf16(Bt[n][k], At[m][k], acc[ai][bj][m][n], 0, 0, 0); __builtin_amdgcn_s_setprio(0); } while (0)
; #define PG8_WAIT_V(n) asm volatile("s_waitcnt vmcnt(" #n ")" ::: "memory")
; #define PG8_WAIT_L(n) asm volatile("s_waitcnt lgkmcnt(" #n ")" ::: "memory")
; #define PG8_BAR __builtin_amdgcn_s_barrier()
; #define PG8_SCHED __builtin_amdgcn_sched_barrier(0)
; template <class Epi, class Sched, bool ALIGN_EPI = false, bool SP2 = false>
; __device__ __forceinline__ void gemm_phase(PG8_LAS unsigned char* lds, const Gemm g, const Sched& S, const Epi& E, int tid_in) {
;     ...
;         for (int t = 0; t < nt; t += 2) {
;             const bool last = (t == nt - 2);
;             const char* a1 = cA + (size_t)(t + 1) * kstep;
;             const char* a2 = last ? nA : cA + (size_t)(t + 2) * kstep; const char* b2 = last ? nB : cB + (size_t)(t + 2) * kstep;
;             const char* a3 = a2 + kstep; const char* b3 = b2 + kstep;
;     ...
;             PG8_LDA(At, 1, 1); PG8_STAGE(PG8_SB(1, 0), b3, voffB); PG8_STAGE(PG8_SB(1, 1), b3 + hstep, voffB); PG8_STAGE(PG8_SA(1, 0), a3, voffA);
;             PG8_WAIT_V(8); PG8_WAIT_L(0); PG8_BAR; PG8_MMA(1, 0, At, B0); PG8_MMA(1, 1, At, B1); PG8_BAR; PG8_SCHED;
;     ...
;         if constexpr (ALIGN_EPI) { if (wr == 0) PG8_BAR; }
	s_add_i32 s3, s3, s1
	v_lshl_add_u64 v[240:241], v[244:245], 0, s[70:71]
	s_mov_b32 m0, s3
	ds_read_b128 v[208:211], v175 offset:49152
	ds_read_b128 v[212:215], v175 offset:50176
	ds_read_b128 v[216:219], v175 offset:51200
	ds_read_b128 v[220:223], v175 offset:52224
	ds_read_b128 v[224:227], v175 offset:53248
	ds_read_b128 v[228:231], v175 offset:54272
	ds_read_b128 v[232:235], v175 offset:55296
	ds_read_b128 v[236:239], v175 offset:56320
	global_load_lds_dwordx4 v[240:241], off
	v_lshl_add_u64 v[240:241], v[246:247], 0, s[70:71]
	s_add_i32 m0, s3, 0x2000
	s_add_i32 s3, s13, s1
	global_load_lds_dwordx4 v[240:241], off
	v_lshl_add_u64 v[240:241], v[242:243], 0, s[86:87]
	v_lshl_add_u64 v[242:243], v[240:241], 0, v[128:129]
	s_mov_b32 m0, s3
	v_lshl_add_u64 v[240:241], v[240:241], 0, v[144:145]
	global_load_lds_dwordx4 v[242:243], off
	s_add_i32 m0, s3, 0x2000
	s_nop 0
	global_load_lds_dwordx4 v[240:241], off
	v_lshl_add_u64 v[240:241], v[248:249], 0, s[70:71]
	s_mov_b32 m0, s20
	s_nop 0
	global_load_lds_dwordx4 v[240:241], off
	v_lshl_add_u64 v[240:241], v[250:251], 0, s[70:71]
	s_mov_b32 m0, s21
	s_nop 0
	global_load_lds_dwordx4 v[240:241], off
	s_waitcnt vmcnt(8) lgkmcnt(0)
	s_barrier
	s_setprio 1
	v_mfma_f32_16x16x32_bf16 v[60:63], v[176:179], v[208:211], v[60:63]
	v_mfma_f32_16x16x32_bf16 v[56:59], v[184:187], v[208:211], v[56:59]
	v_mfma_f32_16x16x32_bf16 v[52:55], v[176:179], v[216:219], v[52:55]
	v_mfma_f32_16x16x32_bf16 v[44:47], v[184:187], v[216:219], v[44:47]
	v_mfma_f32_16x16x32_bf16 v[36:39], v[176:179], v[224:227], v[36:39]
	v_mfma_f32_16x16x32_bf16 v[28:31], v[184:187], v[224:227], v[28:31]
	v_mfma_f32_16x16x32_bf16 v[20:23], v[176:179], v[232:235], v[20:23]
	v_mfma_f32_16x16x32_bf16 v[12:15], v[184:187], v[232:235], v[12:15]
	v_mfma_f32_16x16x32_bf16 v[60:63], v[180:183], v[212:215], v[60:63]
	v_mfma_f32_16x16x32_bf16 v[56:59], v[188:191], v[212:215], v[56:59]
	v_mfma_f32_16x16x32_bf16 v[52:55], v[180:183], v[220:223], v[52:55]
	v_mfma_f32_16x16x32_bf16 v[44:47], v[188:191], v[220:223], v[44:47]
	v_mfma_f32_16x16x32_bf16 v[36:39], v[180:183], v[228:231], v[36:39]
	v_mfma_f32_16x16x32_bf16 v[28:31], v[188:191], v[228:231], v[28:31]
	v_mfma_f32_16x16x32_bf16 v[20:23], v[180:183], v[236:239], v[20:23]
	v_mfma_f32_16x16x32_bf16 v[12:15], v[188:191], v[236:239], v[12:15]
	s_setprio 0
	s_setprio 1
	v_mfma_f32_16x16x32_bf16 v[48:51], v[192:195], v[208:211], v[48:51]
	v_mfma_f32_16x16x32_bf16 v[40:43], v[200:203], v[208:211], v[40:43]
	v_mfma_f32_16x16x32_bf16 v[32:35], v[192:195], v[216:219], v[32:35]
	v_mfma_f32_16x16x32_bf16 v[24:27], v[200:203], v[216:219], v[24:27]
	v_mfma_f32_16x16x32_bf16 v[16:19], v[192:195], v[224:227], v[16:19]
	v_mfma_f32_16x16x32_bf16 v[8:11], v[200:203], v[224:227], v[8:11]
	v_mfma_f32_16x16x32_bf16 v[4:7], v[192:195], v[232:235], v[4:7]
	v_mfma_f32_16x16x32_bf16 v[0:3], v[200:203], v[232:235], v[0:3]
	v_mfma_f32_16x16x32_bf16 v[48:51], v[196:199], v[212:215], v[48:51]
	v_mfma_f32_16x16x32_bf16 v[40:43], v[204:207], v[212:215], v[40:43]
	v_mfma_f32_16x16x32_bf16 v[32:35], v[196:199], v[220:223], v[32:35]
	v_mfma_f32_16x16x32_bf16 v[24:27], v[204:207], v[220:223], v[24:27]
	v_mfma_f32_16x16x32_bf16 v[16:19], v[196:199], v[228:231], v[16:19]
	v_mfma_f32_16x16x32_bf16 v[8:11], v[204:207], v[228:231], v[8:11]
	v_mfma_f32_16x16x32_bf16 v[4:7], v[196:199], v[236:239], v[4:7]
	v_mfma_f32_16x16x32_bf16 v[0:3], v[204:207], v[236:239], v[0:3]
	s_setprio 0
	s_barrier
	s_add_i32 s2, s2, 2
	v_lshl_add_u64 v[164:165], v[164:165], 0, s[82:83]
	s_cmp_gt_u32 s2, 29
	v_lshl_add_u64 v[166:167], v[166:167], 0, s[82:83]
	s_cbranch_scc0 .LBB0_405
	s_and_b64 vcc, exec, s[10:11]
	s_cbranch_vccz .LBB0_408
	s_barrier

; #define PG8_STAGE(bufoff, gbase, voff) do { _Pragma("unroll") for (int _i = 0; _i < 2; ++_i) \
;         __builtin_amdgcn_global_load_lds((const unsigned*)((const char*)(gbase) + (voff)[_i]), (PG8_LAS unsigned*)(lds + (bufoff) + ldsw + _i * 8192), 16, 0, 0); } while (0)
; #define PG8_LDA(dst, b, h) do { _Pragma("unroll") for (int m = 0; m < 4; ++m) _Pragma("unroll") for (int k = 0; k < 2; ++k) dst[m][k] = *(const PG8_LAS bf16x8*)(lds + PG8_SA(b, h) + aoff + m * 2048 + k * 1024); } while (0)
; #define PG8_LDB(dst, b, h) do { _Pragma("unroll") for (int n = 0; n < 2; ++n) _Pragma("unroll") for (int k = 0; k < 2; ++k) dst[n][k] = *(const PG8_LAS bf16x8*)(lds + PG8_SB(b, h) + boff + n * 2048 + k * 1024); } while (0)
; #define PG8_MMA(ai, bj, At, Bt) do { __builtin_amdgcn_s_setprio(1); _Pragma("unroll") for (int m = 0; m < 4; ++m) _Pragma("unroll") for (int n = 0; n < 2; ++n) _Pragma("unroll") for (int k = 0; k < 2; ++k) \
;         acc[ai][bj][m][n] = __builtin_amdgcn_mfma_f32_16x16x32_bf16(Bt[n][k], At[m][k], acc[ai][bj][m][n], 0, 0, 0); __builtin_amdgcn_s_setprio(0); } while (0)
; #define PG8_WAIT_V(n) asm volatile("s_waitcnt vmcnt(" #n ")" ::: "memory")
; #define PG8_WAIT_L(n) asm volatile("s_waitcnt lgkmcnt(" #n ")" ::: "memory")
; #define PG8_BAR __builtin_amdgcn_s_barrier()
; #define PG8_SCHED __builtin_amdgcn_sched_barrier(0)
; template <class Epi, class Sched, bool ALIGN_EPI = false, bool SP2 = false>
; __device__ __forceinline__ void gemm_phase(PG8_LAS unsigned char* lds, const Gemm g, const Sched& S, const Epi& E, int tid_in) {
;     ...
;             const bool last = (t == nt - 2);
;             const char* a1 = cA + (size_t)(t + 1) * kstep;
;             const char* a2 = last ? nA : cA + (size_t)(t + 2) * kstep; const char* b2 = last ? nB : cB + (size_t)(t + 2) * kstep;
;             const char* a3 = a2 + kstep; const char* b3 = b2 + kstep;
;             if (last && has_next) S.a_ready(nxt);
;             if constexpr (SP2) {
;             PG8_LDB(B0, 0, 0); PG8_LDB(B1, 0, 1); PG8_SCHED; PG8_LDA(At, 0, 0); PG8_STAGE(PG8_SA(1, 1), a1 + hstep, voffA);
;             PG8_WAIT_V(8); PG8_WAIT_L(0); PG8_BAR; PG8_MMA(0, 0, At, B0); PG8_MMA(0, 1, At, B1); PG8_BAR; PG8_SCHED;
;             PG8_LDA(At, 0, 1); PG8_STAGE(PG8_SB(0, 0), b2, voffB); PG8_STAGE(PG8_SB(0, 1), b2 + hstep, voffB); PG8_STAGE(PG8_SA(0, 0), a2, voffA);
.LBB0_588:
	s_cmp_eq_u32 s2, 28
	s_cselect_b64 vcc, -1, 0
	s_add_i32 s3, 0, 0x10000
	s_add_i32 s11, 0, 0x14000
	v_lshl_add_u64 v[176:177], v[166:167], 0, s[52:53]
	v_add_u32_e32 v188, s3, v168
	v_add_u32_e32 v204, s11, v168
	v_cndmask_b32_e32 v241, v177, v131, vcc
	v_cndmask_b32_e32 v240, v176, v160, vcc
	ds_read_b128 v[176:179], v188
	ds_read_b128 v[180:183], v188 offset:1024
	ds_read_b128 v[184:187], v188 offset:2048
	ds_read_b128 v[188:191], v188 offset:3072
	ds_read_b128 v[192:195], v204
	ds_read_b128 v[196:199], v204 offset:1024
	ds_read_b128 v[200:203], v204 offset:2048
	ds_read_b128 v[204:207], v204 offset:3072
	v_cndmask_b32_e32 v243, v165, v161, vcc
	v_cndmask_b32_e32 v242, v164, v162, vcc
	v_lshl_add_u64 v[244:245], v[166:167], 0, v[154:155]
	s_add_i32 m0, s15, 0xc000
	ds_read_b128 v[208:211], v175
	ds_read_b128 v[212:215], v175 offset:1024
	ds_read_b128 v[216:219], v175 offset:2048
	ds_read_b128 v[220:223], v175 offset:3072
	ds_read_b128 v[224:227], v175 offset:4096
	ds_read_b128 v[228:231], v175 offset:5120
	ds_read_b128 v[232:235], v175 offset:6144
	ds_read_b128 v[236:239], v175 offset:7168
	global_load_lds_dwordx4 v[244:245], off
	v_lshl_add_u64 v[244:245], v[166:167], 0, v[152:153]
	s_add_i32 m0, s15, 0xe000
	s_nop 0
	global_load_lds_dwordx4 v[244:245], off
	s_waitcnt vmcnt(8) lgkmcnt(0)
	s_barrier
	s_setprio 1
	v_mfma_f32_16x16x32_bf16 v[124:127], v[176:179], v[208:211], v[124:127]
	v_mfma_f32_16x16x32_bf16 v[116:119], v[184:187], v[208:211], v[116:119]
	v_mfma_f32_16x16x32_bf16 v[108:111], v[176:179], v[216:219], v[108:111]
	v_mfma_f32_16x16x32_bf16 v[100:103], v[184:187], v[216:219], v[100:103]
	v_mfma_f32_16x16x32_bf16 v[92:95], v[176:179], v[224:227], v[92:95]
	v_mfma_f32_16x16x32_bf16 v[84:87], v[184:187], v[224:227], v[84:87]
	v_mfma_f32_16x16x32_bf16 v[76:79], v[176:179], v[232:235], v[76:79]
	v_mfma_f32_16x16x32_bf16 v[68:71], v[184:187], v[232:235], v[68:71]
	v_mfma_f32_16x16x32_bf16 v[124:127], v[180:183], v[212:215], v[124:127]
	v_mfma_f32_16x16x32_bf16 v[116:119], v[188:191], v[212:215], v[116:119]
	v_mfma_f32_16x16x32_bf16 v[108:111], v[180:183], v[220:223], v[108:111]
	v_mfma_f32_16x16x32_bf16 v[100:103], v[188:191], v[220:223], v[100:103]
	v_mfma_f32_16x16x32_bf16 v[92:95], v[180:183], v[228:231], v[92:95]
	v_mfma_f32_16x16x32_bf16 v[84:87], v[188:191], v[228:231], v[84:87]
	v_mfma_f32_16x16x32_bf16 v[76:79], v[180:183], v[236:239], v[76:79]
	v_mfma_f32_16x16x32_bf16 v[68:71], v[188:191], v[236:239], v[68:71]
	s_setprio 0
	s_setprio 1
	v_mfma_f32_16x16x32_bf16 v[120:123], v[192:195], v[208:211], v[120:123]
	v_mfma_f32_16x16x32_bf16 v[112:115], v[200:203], v[208:211], v[112:115]
	v_mfma_f32_16x16x32_bf16 v[104:107], v[192:195], v[216:219], v[104:107]
	v_mfma_f32_16x16x32_bf16 v[96:99], v[200:203], v[216:219], v[96:99]
	v_mfma_f32_16x16x32_bf16 v[88:91], v[192:195], v[224:227], v[88:91]
	v_mfma_f32_16x16x32_bf16 v[80:83], v[200:203], v[224:227], v[80:83]
	v_mfma_f32_16x16x32_bf16 v[72:75], v[192:195], v[232:235], v[72:75]
	v_mfma_f32_16x16x32_bf16 v[64:67], v[200:203], v[232:235], v[64:67]
	v_mfma_f32_16x16x32_bf16 v[120:123], v[196:199], v[212:215], v[120:123]
	v_mfma_f32_16x16x32_bf16 v[112:115], v[204:207], v[212:215], v[112:115]
	v_mfma_f32_16x16x32_bf16 v[104:107], v[196:199], v[220:223], v[104:107]
	v_mfma_f32_16x16x32_bf16 v[96:99], v[204:207], v[220:223], v[96:99]
	v_mfma_f32_16x16x32_bf16 v[88:91], v[196:199], v[228:231], v[88:91]
	v_mfma_f32_16x16x32_bf16 v[80:83], v[204:207], v[228:231], v[80:83]
	v_mfma_f32_16x16x32_bf16 v[72:75], v[196:199], v[236:239], v[72:75]
	v_mfma_f32_16x16x32_bf16 v[64:67], v[204:207], v[236:239], v[64:67]
	s_setprio 0
	s_barrier
	s_add_i32 s3, s3, s14
	v_lshl_add_u64 v[244:245], v[242:243], 0, v[128:129]
	s_mov_b32 m0, s3
	ds_read_b128 v[208:211], v175 offset:16384
	ds_read_b128 v[212:215], v175 offset:17408
	ds_read_b128 v[216:219], v175 offset:18432
	ds_read_b128 v[220:223], v175 offset:19456
	ds_read_b128 v[224:227], v175 offset:20480
	ds_read_b128 v[228:231], v175 offset:21504
	ds_read_b128 v[232:235], v175 offset:22528
	ds_read_b128 v[236:239], v175 offset:23552
	global_load_lds_dwordx4 v[244:245], off
	v_lshl_add_u64 v[246:247], v[242:243], 0, v[144:145]
	s_add_i32 m0, s3, 0x2000
	v_lshl_add_u64 v[248:249], v[242:243], 0, s[98:99]
	s_add_i32 s3, s11, s14
	global_load_lds_dwordx4 v[246:247], off
	v_lshl_add_u64 v[250:251], v[248:249], 0, v[128:129]
	s_mov_b32 m0, s3
	v_lshl_add_u64 v[248:249], v[248:249], 0, v[144:145]
	global_load_lds_dwordx4 v[250:251], off
	s_add_i32 m0, s3, 0x2000
	v_lshl_add_u64 v[250:251], v[240:241], 0, v[146:147]
	global_load_lds_dwordx4 v[248:249], off
	v_lshl_add_u64 v[248:249], v[240:241], 0, v[148:149]
	s_mov_b32 m0, s15
	s_nop 0
	global_load_lds_dwordx4 v[248:249], off
	s_mov_b32 m0, s16
	s_nop 0
	global_load_lds_dwordx4 v[250:251], off
	s_waitcnt vmcnt(8) lgkmcnt(0)
	s_barrier
; #define PG8_STAGE(bufoff, gbase, voff) do { _Pragma("unroll") for (int _i = 0; _i < 2; ++_i) \
;         __builtin_amdgcn_global_load_lds((const unsigned*)((const char*)(gbase) + (voff)[_i]), (PG8_LAS unsigned*)(lds + (bufoff) + ldsw + _i * 8192), 16, 0, 0); } while (0)
; #define PG8_LDA(dst, b, h) do { _Pragma("unroll") for (int m = 0; m < 4; ++m) _Pragma("unroll") for (int k = 0; k < 2; ++k) dst[m][k] = *(const PG8_LAS bf16x8*)(lds + PG8_SA(b, h) + aoff + m * 2048 + k * 1024); } while (0)
; #define PG8_LDB(dst, b, h) do { _Pragma("unroll") for (int n = 0; n < 2; ++n) _Pragma("unroll") for (int k = 0; k < 2; ++k) dst[n][k] = *(const PG8_LAS bf16x8*)(lds + PG8_SB(b, h) + boff + n * 2048 + k * 1024); } while (0)
; #define PG8_MMA(ai, bj, At, Bt) do { __builtin_amdgcn_s_setprio(1); _Pragma("unroll") for (int m = 0; m < 4; ++m) _Pragma("unroll") for (int n = 0; n < 2; ++n) _Pragma("unroll") for (int k = 0; k < 2; ++k) \
;         acc[ai][bj][m][n] = __builtin_amdgcn_mfma_f32_16x16x32_bf16(Bt[n][k], At[m][k], acc[ai][bj][m][n], 0, 0, 0); __builtin_amdgcn_s_setprio(0); } while (0)
; #define PG8_WAIT_V(n) asm volatile("s_waitcnt vmcnt(" #n ")" ::: "memory")
; #define PG8_WAIT_L(n) asm volatile("s_waitcnt lgkmcnt(" #n ")" ::: "memory")
; #define PG8_BAR __builtin_amdgcn_s_barrier()
; #define PG8_SCHED __builtin_amdgcn_sched_barrier(0)
; template <class Epi, class Sched, bool ALIGN_EPI = false, bool SP2 = false>
; __device__ __forceinline__ void gemm_phase(PG8_LAS unsigned char* lds, const Gemm g, const Sched& S, const Epi& E, int tid_in) {
;     ...
;             PG8_WAIT_V(8); PG8_WAIT_L(0); PG8_BAR; PG8_MMA(1, 0, At, B0); PG8_MMA(1, 1, At, B1); PG8_BAR; PG8_SCHED;
;             PG8_LDB(B0, 1, 0); PG8_LDB(B1, 1, 1); PG8_SCHED; PG8_LDA(At, 1, 0); PG8_STAGE(PG8_SA(0, 1), a2 + hstep, voffA);
;             PG8_WAIT_V(8); PG8_WAIT_L(0); PG8_BAR; PG8_MMA(0, 0, At, B0); PG8_MMA(0, 1, At, B1); PG8_BAR; PG8_SCHED;
	s_setprio 1
	v_mfma_f32_16x16x32_bf16 v[60:63], v[176:179], v[208:211], v[60:63]
	v_mfma_f32_16x16x32_bf16 v[52:55], v[184:187], v[208:211], v[52:55]
	v_mfma_f32_16x16x32_bf16 v[44:47], v[176:179], v[216:219], v[44:47]
	v_mfma_f32_16x16x32_bf16 v[36:39], v[184:187], v[216:219], v[36:39]
	v_mfma_f32_16x16x32_bf16 v[28:31], v[176:179], v[224:227], v[28:31]
	v_mfma_f32_16x16x32_bf16 v[20:23], v[184:187], v[224:227], v[20:23]
	v_mfma_f32_16x16x32_bf16 v[12:15], v[176:179], v[232:235], v[12:15]
	v_mfma_f32_16x16x32_bf16 v[4:7], v[184:187], v[232:235], v[4:7]
	v_mfma_f32_16x16x32_bf16 v[60:63], v[180:183], v[212:215], v[60:63]
	v_mfma_f32_16x16x32_bf16 v[52:55], v[188:191], v[212:215], v[52:55]
	v_mfma_f32_16x16x32_bf16 v[44:47], v[180:183], v[220:223], v[44:47]
	v_mfma_f32_16x16x32_bf16 v[36:39], v[188:191], v[220:223], v[36:39]
	v_mfma_f32_16x16x32_bf16 v[28:31], v[180:183], v[228:231], v[28:31]
	v_mfma_f32_16x16x32_bf16 v[20:23], v[188:191], v[228:231], v[20:23]
	v_mfma_f32_16x16x32_bf16 v[12:15], v[180:183], v[236:239], v[12:15]
	v_mfma_f32_16x16x32_bf16 v[4:7], v[188:191], v[236:239], v[4:7]
	s_setprio 0
	s_setprio 1
	v_mfma_f32_16x16x32_bf16 v[56:59], v[192:195], v[208:211], v[56:59]
	v_mfma_f32_16x16x32_bf16 v[48:51], v[200:203], v[208:211], v[48:51]
	v_mfma_f32_16x16x32_bf16 v[40:43], v[192:195], v[216:219], v[40:43]
	v_mfma_f32_16x16x32_bf16 v[32:35], v[200:203], v[216:219], v[32:35]
	v_mfma_f32_16x16x32_bf16 v[24:27], v[192:195], v[224:227], v[24:27]
	v_mfma_f32_16x16x32_bf16 v[16:19], v[200:203], v[224:227], v[16:19]
	v_mfma_f32_16x16x32_bf16 v[8:11], v[192:195], v[232:235], v[8:11]
	v_mfma_f32_16x16x32_bf16 v[0:3], v[200:203], v[232:235], v[0:3]
	v_mfma_f32_16x16x32_bf16 v[56:59], v[196:199], v[212:215], v[56:59]
	v_mfma_f32_16x16x32_bf16 v[48:51], v[204:207], v[212:215], v[48:51]
	v_mfma_f32_16x16x32_bf16 v[40:43], v[196:199], v[220:223], v[40:43]
	v_mfma_f32_16x16x32_bf16 v[32:35], v[204:207], v[220:223], v[32:35]
	v_mfma_f32_16x16x32_bf16 v[24:27], v[196:199], v[228:231], v[24:27]
	v_mfma_f32_16x16x32_bf16 v[16:19], v[204:207], v[228:231], v[16:19]
	v_mfma_f32_16x16x32_bf16 v[8:11], v[196:199], v[236:239], v[8:11]
	v_mfma_f32_16x16x32_bf16 v[0:3], v[204:207], v[236:239], v[0:3]
	s_setprio 0
	s_barrier
	s_add_i32 s3, 0, 0x18000
	s_add_i32 s11, 0, 0x1c000
	v_add_u32_e32 v188, s3, v168
	v_add_u32_e32 v204, s11, v168
	ds_read_b128 v[176:179], v188
	ds_read_b128 v[180:183], v188 offset:1024
	ds_read_b128 v[184:187], v188 offset:2048
	ds_read_b128 v[188:191], v188 offset:3072
	ds_read_b128 v[192:195], v204
	ds_read_b128 v[196:199], v204 offset:1024
	ds_read_b128 v[200:203], v204 offset:2048
	ds_read_b128 v[204:207], v204 offset:3072
	v_lshl_add_u64 v[240:241], v[240:241], 0, s[98:99]
	s_mov_b32 m0, s17
	v_lshl_add_u64 v[252:253], v[240:241], 0, v[148:149]
	ds_read_b128 v[208:211], v175 offset:32768
	ds_read_b128 v[212:215], v175 offset:33792
	ds_read_b128 v[216:219], v175 offset:34816
	ds_read_b128 v[220:223], v175 offset:35840
	ds_read_b128 v[224:227], v175 offset:36864
	ds_read_b128 v[228:231], v175 offset:37888
	ds_read_b128 v[232:235], v175 offset:38912
	ds_read_b128 v[236:239], v175 offset:39936
	global_load_lds_dwordx4 v[252:253], off
	v_lshl_add_u64 v[240:241], v[240:241], 0, v[146:147]
	s_mov_b32 m0, s18
	s_nop 0
	global_load_lds_dwordx4 v[240:241], off
	s_waitcnt vmcnt(8) lgkmcnt(0)
	s_barrier
	s_setprio 1
	v_mfma_f32_16x16x32_bf16 v[124:127], v[176:179], v[208:211], v[124:127]
	v_mfma_f32_16x16x32_bf16 v[116:119], v[184:187], v[208:211], v[116:119]
	v_mfma_f32_16x16x32_bf16 v[108:111], v[176:179], v[216:219], v[108:111]
	v_mfma_f32_16x16x32_bf16 v[100:103], v[184:187], v[216:219], v[100:103]
	v_mfma_f32_16x16x32_bf16 v[92:95], v[176:179], v[224:227], v[92:95]
	v_mfma_f32_16x16x32_bf16 v[84:87], v[184:187], v[224:227], v[84:87]
	v_mfma_f32_16x16x32_bf16 v[76:79], v[176:179], v[232:235], v[76:79]
	v_mfma_f32_16x16x32_bf16 v[68:71], v[184:187], v[232:235], v[68:71]
	v_mfma_f32_16x16x32_bf16 v[124:127], v[180:183], v[212:215], v[124:127]
	v_mfma_f32_16x16x32_bf16 v[116:119], v[188:191], v[212:215], v[116:119]
	v_mfma_f32_16x16x32_bf16 v[108:111], v[180:183], v[220:223], v[108:111]
	v_mfma_f32_16x16x32_bf16 v[100:103], v[188:191], v[220:223], v[100:103]
	v_mfma_f32_16x16x32_bf16 v[92:95], v[180:183], v[228:231], v[92:95]
	v_mfma_f32_16x16x32_bf16 v[84:87], v[188:191], v[228:231], v[84:87]
	v_mfma_f32_16x16x32_bf16 v[76:79], v[180:183], v[236:239], v[76:79]
	v_mfma_f32_16x16x32_bf16 v[68:71], v[188:191], v[236:239], v[68:71]
	s_setprio 0
	s_setprio 1
	v_mfma_f32_16x16x32_bf16 v[120:123], v[192:195], v[208:211], v[120:123]
	v_mfma_f32_16x16x32_bf16 v[112:115], v[200:203], v[208:211], v[112:115]
	v_mfma_f32_16x16x32_bf16 v[104:107], v[192:195], v[216:219], v[104:107]
	v_mfma_f32_16x16x32_bf16 v[96:99], v[200:203], v[216:219], v[96:99]
	v_mfma_f32_16x16x32_bf16 v[88:91], v[192:195], v[224:227], v[88:91]
	v_mfma_f32_16x16x32_bf16 v[80:83], v[200:203], v[224:227], v[80:83]
	v_mfma_f32_16x16x32_bf16 v[72:75], v[192:195], v[232:235], v[72:75]
	v_mfma_f32_16x16x32_bf16 v[64:67], v[200:203], v[232:235], v[64:67]
	v_mfma_f32_16x16x32_bf16 v[120:123], v[196:199], v[212:215], v[120:123]
	v_mfma_f32_16x16x32_bf16 v[112:115], v[204:207], v[212:215], v[112:115]
	v_mfma_f32_16x16x32_bf16 v[104:107], v[196:199], v[220:223], v[104:107]
	v_mfma_f32_16x16x32_bf16 v[96:99], v[204:207], v[220:223], v[96:99]
	v_mfma_f32_16x16x32_bf16 v[88:91], v[196:199], v[228:231], v[88:91]
	v_mfma_f32_16x16x32_bf16 v[80:83], v[204:207], v[228:231], v[80:83]
	v_mfma_f32_16x16x32_bf16 v[72:75], v[196:199], v[236:239], v[72:75]
	v_mfma_f32_16x16x32_bf16 v[64:67], v[204:207], v[236:239], v[64:67]
	s_setprio 0
	s_barrier
; #define PG8_STAGE(bufoff, gbase, voff) do { _Pragma("unroll") for (int _i = 0; _i < 2; ++_i) \
;         __builtin_amdgcn_global_load_lds((const unsigned*)((const char*)(gbase) + (voff)[_i]), (PG8_LAS unsigned*)(lds + (bufoff) + ldsw + _i * 8192), 16, 0, 0); } while (0)
; #define PG8_LDA(dst, b, h) do { _Pragma("unroll") for (int m = 0; m < 4; ++m) _Pragma("unroll") for (int k = 0; k < 2; ++k) dst[m][k] = *(const PG8_LAS bf16x8*)(lds + PG8_SA(b, h) + aoff + m * 2048 + k * 1024); } while (0)
; #define PG8_MMA(ai, bj, At, Bt) do { __builtin_amdgcn_s_setprio(1); _Pragma("unroll") for (int m = 0; m < 4; ++m) _Pragma("unroll") for (int n = 0; n < 2; ++n) _Pragma("unroll") for (int k = 0; k < 2; ++k) \
;         acc[ai][bj][m][n] = __builtin_amdgcn_mfma_f32_16x16x32_bf16(Bt[n][k], At[m][k], acc[ai][bj][m][n], 0, 0, 0); __builtin_amdgcn_s_setprio(0); } while (0)
; #define PG8_WAIT_V(n) asm volatile("s_waitcnt vmcnt(" #n ")" ::: "memory")
; #define PG8_WAIT_L(n) asm volatile("s_waitcnt lgkmcnt(" #n ")" ::: "memory")
; #define PG8_BAR __builtin_amdgcn_s_barrier()
; #define PG8_SCHED __builtin_amdgcn_sched_barrier(0)
; template <class Epi, class Sched, bool ALIGN_EPI = false, bool SP2 = false>
; __device__ __forceinline__ void gemm_phase(PG8_LAS unsigned char* lds, const Gemm g, const Sched& S, const Epi& E, int tid_in) {
;     ...
;         for (int t = 0; t < nt; t += 2) {
;             const bool last = (t == nt - 2);
;             const char* a1 = cA + (size_t)(t + 1) * kstep;
;             const char* a2 = last ? nA : cA + (size_t)(t + 2) * kstep; const char* b2 = last ? nB : cB + (size_t)(t + 2) * kstep;
;             const char* a3 = a2 + kstep; const char* b3 = b2 + kstep;
;     ...
;             PG8_LDA(At, 1, 1); PG8_STAGE(PG8_SB(1, 0), b3, voffB); PG8_STAGE(PG8_SB(1, 1), b3 + hstep, voffB); PG8_STAGE(PG8_SA(1, 0), a3, voffA);
;             PG8_WAIT_V(8); PG8_WAIT_L(0); PG8_BAR; PG8_MMA(1, 0, At, B0); PG8_MMA(1, 1, At, B1); PG8_BAR; PG8_SCHED;
;     ...
;         if constexpr (ALIGN_EPI) { if (wr == 0) PG8_BAR; }
	s_add_i32 s3, s3, s14
	v_lshl_add_u64 v[240:241], v[244:245], 0, s[70:71]
	s_mov_b32 m0, s3
	ds_read_b128 v[208:211], v175 offset:49152
	ds_read_b128 v[212:215], v175 offset:50176
	ds_read_b128 v[216:219], v175 offset:51200
	ds_read_b128 v[220:223], v175 offset:52224
	ds_read_b128 v[224:227], v175 offset:53248
	ds_read_b128 v[228:231], v175 offset:54272
	ds_read_b128 v[232:235], v175 offset:55296
	ds_read_b128 v[236:239], v175 offset:56320
	global_load_lds_dwordx4 v[240:241], off
	v_lshl_add_u64 v[240:241], v[246:247], 0, s[70:71]
	s_add_i32 m0, s3, 0x2000
	s_add_i32 s3, s11, s14
	global_load_lds_dwordx4 v[240:241], off
	v_lshl_add_u64 v[240:241], v[242:243], 0, s[86:87]
	v_lshl_add_u64 v[242:243], v[240:241], 0, v[128:129]
	s_mov_b32 m0, s3
	v_lshl_add_u64 v[240:241], v[240:241], 0, v[144:145]
	global_load_lds_dwordx4 v[242:243], off
	s_add_i32 m0, s3, 0x2000
	s_nop 0
	global_load_lds_dwordx4 v[240:241], off
	v_lshl_add_u64 v[240:241], v[248:249], 0, s[70:71]
	s_mov_b32 m0, s19
	s_nop 0
	global_load_lds_dwordx4 v[240:241], off
	v_lshl_add_u64 v[240:241], v[250:251], 0, s[70:71]
	s_mov_b32 m0, s1
	s_nop 0
	global_load_lds_dwordx4 v[240:241], off
	s_waitcnt vmcnt(8) lgkmcnt(0)
	s_barrier
	s_setprio 1
	v_mfma_f32_16x16x32_bf16 v[60:63], v[176:179], v[208:211], v[60:63]
	v_mfma_f32_16x16x32_bf16 v[52:55], v[184:187], v[208:211], v[52:55]
	v_mfma_f32_16x16x32_bf16 v[44:47], v[176:179], v[216:219], v[44:47]
	v_mfma_f32_16x16x32_bf16 v[36:39], v[184:187], v[216:219], v[36:39]
	v_mfma_f32_16x16x32_bf16 v[28:31], v[176:179], v[224:227], v[28:31]
	v_mfma_f32_16x16x32_bf16 v[20:23], v[184:187], v[224:227], v[20:23]
	v_mfma_f32_16x16x32_bf16 v[12:15], v[176:179], v[232:235], v[12:15]
	v_mfma_f32_16x16x32_bf16 v[4:7], v[184:187], v[232:235], v[4:7]
	v_mfma_f32_16x16x32_bf16 v[60:63], v[180:183], v[212:215], v[60:63]
	v_mfma_f32_16x16x32_bf16 v[52:55], v[188:191], v[212:215], v[52:55]
	v_mfma_f32_16x16x32_bf16 v[44:47], v[180:183], v[220:223], v[44:47]
	v_mfma_f32_16x16x32_bf16 v[36:39], v[188:191], v[220:223], v[36:39]
	v_mfma_f32_16x16x32_bf16 v[28:31], v[180:183], v[228:231], v[28:31]
	v_mfma_f32_16x16x32_bf16 v[20:23], v[188:191], v[228:231], v[20:23]
	v_mfma_f32_16x16x32_bf16 v[12:15], v[180:183], v[236:239], v[12:15]
	v_mfma_f32_16x16x32_bf16 v[4:7], v[188:191], v[236:239], v[4:7]
	s_setprio 0
	s_setprio 1
	v_mfma_f32_16x16x32_bf16 v[56:59], v[192:195], v[208:211], v[56:59]
	v_mfma_f32_16x16x32_bf16 v[48:51], v[200:203], v[208:211], v[48:51]
	v_mfma_f32_16x16x32_bf16 v[40:43], v[192:195], v[216:219], v[40:43]
	v_mfma_f32_16x16x32_bf16 v[32:35], v[200:203], v[216:219], v[32:35]
	v_mfma_f32_16x16x32_bf16 v[24:27], v[192:195], v[224:227], v[24:27]
	v_mfma_f32_16x16x32_bf16 v[16:19], v[200:203], v[224:227], v[16:19]
	v_mfma_f32_16x16x32_bf16 v[8:11], v[192:195], v[232:235], v[8:11]
	v_mfma_f32_16x16x32_bf16 v[0:3], v[200:203], v[232:235], v[0:3]
	v_mfma_f32_16x16x32_bf16 v[56:59], v[196:199], v[212:215], v[56:59]
	v_mfma_f32_16x16x32_bf16 v[48:51], v[204:207], v[212:215], v[48:51]
	v_mfma_f32_16x16x32_bf16 v[40:43], v[196:199], v[220:223], v[40:43]
	v_mfma_f32_16x16x32_bf16 v[32:35], v[204:207], v[220:223], v[32:35]
	v_mfma_f32_16x16x32_bf16 v[24:27], v[196:199], v[228:231], v[24:27]
	v_mfma_f32_16x16x32_bf16 v[16:19], v[204:207], v[228:231], v[16:19]
	v_mfma_f32_16x16x32_bf16 v[8:11], v[196:199], v[236:239], v[8:11]
	v_mfma_f32_16x16x32_bf16 v[0:3], v[204:207], v[236:239], v[0:3]
	s_setprio 0
	s_barrier
	s_add_i32 s2, s2, 2
	v_lshl_add_u64 v[164:165], v[164:165], 0, s[82:83]
	s_cmp_gt_u32 s2, 29
	v_lshl_add_u64 v[166:167], v[166:167], 0, s[82:83]
	s_cbranch_scc0 .LBB0_588
	s_and_b64 vcc, exec, s[8:9]
	s_cbranch_vccz .LBB0_591
	s_barrier

; #define PG8_STAGE(bufoff, gbase, voff) do { _Pragma("unroll") for (int _i = 0; _i < 2; ++_i) \
;         __builtin_amdgcn_global_load_lds((const unsigned*)((const char*)(gbase) + (voff)[_i]), (PG8_LAS unsigned*)(lds + (bufoff) + ldsw + _i * 8192), 16, 0, 0); } while (0)
; #define PG8_LDA(dst, b, h) do { _Pragma("unroll") for (int m = 0; m < 4; ++m) _Pragma("unroll") for (int k = 0; k < 2; ++k) dst[m][k] = *(const PG8_LAS bf16x8*)(lds + PG8_SA(b, h) + aoff + m * 2048 + k * 1024); } while (0)
; #define PG8_LDB(dst, b, h) do { _Pragma("unroll") for (int n = 0; n < 2; ++n) _Pragma("unroll") for (int k = 0; k < 2; ++k) dst[n][k] = *(const PG8_LAS bf16x8*)(lds + PG8_SB(b, h) + boff + n * 2048 + k * 1024); } while (0)
; #define PG8_MMA(ai, bj, At, Bt) do { __builtin_amdgcn_s_setprio(1); _Pragma("unroll") for (int m = 0; m < 4; ++m) _Pragma("unroll") for (int n = 0; n < 2; ++n) _Pragma("unroll") for (int k = 0; k < 2; ++k) \
;         acc[ai][bj][m][n] = __builtin_amdgcn_mfma_f32_16x16x32_bf16(Bt[n][k], At[m][k], acc[ai][bj][m][n], 0, 0, 0); __builtin_amdgcn_s_setprio(0); } while (0)
; #define PG8_WAIT_V(n) asm volatile("s_waitcnt vmcnt(" #n ")" ::: "memory")
; #define PG8_WAIT_L(n) asm volatile("s_waitcnt lgkmcnt(" #n ")" ::: "memory")
; #define PG8_BAR __builtin_amdgcn_s_barrier()
; #define PG8_SCHED __builtin_amdgcn_sched_barrier(0)
; template <class Epi, class Sched, bool ALIGN_EPI = false, bool SP2 = false>
; __device__ __forceinline__ void gemm_phase(PG8_LAS unsigned char* lds, const Gemm g, const Sched& S, const Epi& E, int tid_in) {
;     ...
;             const bool last = (t == nt - 2);
;             const char* a1 = cA + (size_t)(t + 1) * kstep;
;             const char* a2 = last ? nA : cA + (size_t)(t + 2) * kstep; const char* b2 = last ? nB : cB + (size_t)(t + 2) * kstep;
;             const char* a3 = a2 + kstep; const char* b3 = b2 + kstep;
;             if (last && has_next) S.a_ready(nxt);
;             if constexpr (SP2) {
;             PG8_LDB(B0, 0, 0); PG8_LDB(B1, 0, 1); PG8_SCHED; PG8_LDA(At, 0, 0); PG8_STAGE(PG8_SA(1, 1), a1 + hstep, voffA);
;             PG8_WAIT_V(8); PG8_WAIT_L(0); PG8_BAR; PG8_MMA(0, 0, At, B0); PG8_MMA(0, 1, At, B1); PG8_BAR; PG8_SCHED;
;             PG8_LDA(At, 0, 1); PG8_STAGE(PG8_SB(0, 0), b2, voffB); PG8_STAGE(PG8_SB(0, 1), b2 + hstep, voffB); PG8_STAGE(PG8_SA(0, 0), a2, voffA);
.LBB0_683:
	s_cmpk_eq_i32 s2, 0x54
	s_cselect_b64 vcc, -1, 0
	s_add_i32 s3, 0, 0x10000
	v_add_u32_e32 v169, s3, v166
	s_add_i32 s8, 0, 0x14000
	ds_read_b128 v[176:179], v169
	ds_read_b128 v[180:183], v169 offset:1024
	ds_read_b128 v[184:187], v169 offset:2048
	ds_read_b128 v[188:191], v169 offset:3072
	v_add_u32_e32 v169, s8, v166
	ds_read_b128 v[192:195], v169
	ds_read_b128 v[196:199], v169 offset:1024
	ds_read_b128 v[200:203], v169 offset:2048
	ds_read_b128 v[204:207], v169 offset:3072
	v_lshl_add_u64 v[164:165], v[162:163], 0, s[82:83]
	v_cndmask_b32_e32 v241, v165, v157, vcc
	v_cndmask_b32_e32 v240, v164, v156, vcc
	v_cndmask_b32_e32 v243, v161, v159, vcc
	v_cndmask_b32_e32 v242, v160, v158, vcc
	v_lshl_add_u64 v[244:245], v[162:163], 0, v[154:155]
	s_add_i32 m0, s14, 0xc000
	ds_read_b128 v[208:211], v168
	ds_read_b128 v[212:215], v168 offset:1024
	ds_read_b128 v[216:219], v168 offset:2048
	ds_read_b128 v[220:223], v168 offset:3072
	ds_read_b128 v[224:227], v168 offset:4096
	ds_read_b128 v[228:231], v168 offset:5120
	ds_read_b128 v[232:235], v168 offset:6144
	ds_read_b128 v[236:239], v168 offset:7168
	global_load_lds_dwordx4 v[244:245], off
	v_lshl_add_u64 v[162:163], v[162:163], 0, v[152:153]
	s_add_i32 m0, s14, 0xe000
	s_nop 0
	global_load_lds_dwordx4 v[162:163], off
	s_waitcnt vmcnt(8) lgkmcnt(0)
	s_barrier
	s_setprio 1
	v_mfma_f32_16x16x32_bf16 v[124:127], v[176:179], v[208:211], v[124:127]
	v_mfma_f32_16x16x32_bf16 v[120:123], v[184:187], v[208:211], v[120:123]
	v_mfma_f32_16x16x32_bf16 v[116:119], v[176:179], v[216:219], v[116:119]
	v_mfma_f32_16x16x32_bf16 v[108:111], v[184:187], v[216:219], v[108:111]
	v_mfma_f32_16x16x32_bf16 v[100:103], v[176:179], v[224:227], v[100:103]
	v_mfma_f32_16x16x32_bf16 v[92:95], v[184:187], v[224:227], v[92:95]
	v_mfma_f32_16x16x32_bf16 v[84:87], v[176:179], v[232:235], v[84:87]
	v_mfma_f32_16x16x32_bf16 v[76:79], v[184:187], v[232:235], v[76:79]
	v_mfma_f32_16x16x32_bf16 v[124:127], v[180:183], v[212:215], v[124:127]
	v_mfma_f32_16x16x32_bf16 v[120:123], v[188:191], v[212:215], v[120:123]
	v_mfma_f32_16x16x32_bf16 v[116:119], v[180:183], v[220:223], v[116:119]
	v_mfma_f32_16x16x32_bf16 v[108:111], v[188:191], v[220:223], v[108:111]
	v_mfma_f32_16x16x32_bf16 v[100:103], v[180:183], v[228:231], v[100:103]
	v_mfma_f32_16x16x32_bf16 v[92:95], v[188:191], v[228:231], v[92:95]
	v_mfma_f32_16x16x32_bf16 v[84:87], v[180:183], v[236:239], v[84:87]
	v_mfma_f32_16x16x32_bf16 v[76:79], v[188:191], v[236:239], v[76:79]
	s_setprio 0
	s_setprio 1
	v_mfma_f32_16x16x32_bf16 v[112:115], v[192:195], v[208:211], v[112:115]
	v_mfma_f32_16x16x32_bf16 v[104:107], v[200:203], v[208:211], v[104:107]
	v_mfma_f32_16x16x32_bf16 v[96:99], v[192:195], v[216:219], v[96:99]
	v_mfma_f32_16x16x32_bf16 v[88:91], v[200:203], v[216:219], v[88:91]
	v_mfma_f32_16x16x32_bf16 v[80:83], v[192:195], v[224:227], v[80:83]
	v_mfma_f32_16x16x32_bf16 v[72:75], v[200:203], v[224:227], v[72:75]
	v_mfma_f32_16x16x32_bf16 v[68:71], v[192:195], v[232:235], v[68:71]
	v_mfma_f32_16x16x32_bf16 v[64:67], v[200:203], v[232:235], v[64:67]
	v_mfma_f32_16x16x32_bf16 v[112:115], v[196:199], v[212:215], v[112:115]
	v_mfma_f32_16x16x32_bf16 v[104:107], v[204:207], v[212:215], v[104:107]
	v_mfma_f32_16x16x32_bf16 v[96:99], v[196:199], v[220:223], v[96:99]
	v_mfma_f32_16x16x32_bf16 v[88:91], v[204:207], v[220:223], v[88:91]
	v_mfma_f32_16x16x32_bf16 v[80:83], v[196:199], v[228:231], v[80:83]
	v_mfma_f32_16x16x32_bf16 v[72:75], v[204:207], v[228:231], v[72:75]
	v_mfma_f32_16x16x32_bf16 v[68:71], v[196:199], v[236:239], v[68:71]
	v_mfma_f32_16x16x32_bf16 v[64:67], v[204:207], v[236:239], v[64:67]
	s_setprio 0
	s_barrier
	s_add_i32 s3, s3, s1
	v_lshl_add_u64 v[162:163], v[242:243], 0, v[128:129]
	s_mov_b32 m0, s3
	ds_read_b128 v[208:211], v168 offset:16384
	ds_read_b128 v[212:215], v168 offset:17408
	ds_read_b128 v[216:219], v168 offset:18432
	ds_read_b128 v[220:223], v168 offset:19456
	ds_read_b128 v[224:227], v168 offset:20480
	ds_read_b128 v[228:231], v168 offset:21504
	ds_read_b128 v[232:235], v168 offset:22528
	ds_read_b128 v[236:239], v168 offset:23552
	global_load_lds_dwordx4 v[162:163], off
	v_lshl_add_u64 v[244:245], v[242:243], 0, v[144:145]
	s_add_i32 m0, s3, 0x2000
	v_lshl_add_u64 v[246:247], v[242:243], 0, s[74:75]
	s_add_i32 s3, s8, s1
	global_load_lds_dwordx4 v[244:245], off
	v_lshl_add_u64 v[248:249], v[246:247], 0, v[128:129]
	s_mov_b32 m0, s3
	v_lshl_add_u64 v[246:247], v[246:247], 0, v[144:145]
	global_load_lds_dwordx4 v[248:249], off
	s_add_i32 m0, s3, 0x2000
	v_lshl_add_u64 v[248:249], v[240:241], 0, v[146:147]
	global_load_lds_dwordx4 v[246:247], off
	v_lshl_add_u64 v[246:247], v[240:241], 0, v[148:149]
	s_mov_b32 m0, s14
	s_nop 0
	global_load_lds_dwordx4 v[246:247], off
	s_mov_b32 m0, s15
	s_nop 0
	global_load_lds_dwordx4 v[248:249], off
	s_waitcnt vmcnt(8) lgkmcnt(0)
	s_barrier
; #define PG8_STAGE(bufoff, gbase, voff) do { _Pragma("unroll") for (int _i = 0; _i < 2; ++_i) \
;         __builtin_amdgcn_global_load_lds((const unsigned*)((const char*)(gbase) + (voff)[_i]), (PG8_LAS unsigned*)(lds + (bufoff) + ldsw + _i * 8192), 16, 0, 0); } while (0)
; #define PG8_LDA(dst, b, h) do { _Pragma("unroll") for (int m = 0; m < 4; ++m) _Pragma("unroll") for (int k = 0; k < 2; ++k) dst[m][k] = *(const PG8_LAS bf16x8*)(lds + PG8_SA(b, h) + aoff + m * 2048 + k * 1024); } while (0)
; #define PG8_LDB(dst, b, h) do { _Pragma("unroll") for (int n = 0; n < 2; ++n) _Pragma("unroll") for (int k = 0; k < 2; ++k) dst[n][k] = *(const PG8_LAS bf16x8*)(lds + PG8_SB(b, h) + boff + n * 2048 + k * 1024); } while (0)
; #define PG8_MMA(ai, bj, At, Bt) do { __builtin_amdgcn_s_setprio(1); _Pragma("unroll") for (int m = 0; m < 4; ++m) _Pragma("unroll") for (int n = 0; n < 2; ++n) _Pragma("unroll") for (int k = 0; k < 2; ++k) \
;         acc[ai][bj][m][n] = __builtin_amdgcn_mfma_f32_16x16x32_bf16(Bt[n][k], At[m][k], acc[ai][bj][m][n], 0, 0, 0); __builtin_amdgcn_s_setprio(0); } while (0)
; #define PG8_WAIT_V(n) asm volatile("s_waitcnt vmcnt(" #n ")" ::: "memory")
; #define PG8_WAIT_L(n) asm volatile("s_waitcnt lgkmcnt(" #n ")" ::: "memory")
; #define PG8_BAR __builtin_amdgcn_s_barrier()
; #define PG8_SCHED __builtin_amdgcn_sched_barrier(0)
; template <class Epi, class Sched, bool ALIGN_EPI = false, bool SP2 = false>
; __device__ __forceinline__ void gemm_phase(PG8_LAS unsigned char* lds, const Gemm g, const Sched& S, const Epi& E, int tid_in) {
;     ...
;             PG8_WAIT_V(8); PG8_WAIT_L(0); PG8_BAR; PG8_MMA(1, 0, At, B0); PG8_MMA(1, 1, At, B1); PG8_BAR; PG8_SCHED;
;             PG8_LDB(B0, 1, 0); PG8_LDB(B1, 1, 1); PG8_SCHED; PG8_LDA(At, 1, 0); PG8_STAGE(PG8_SA(0, 1), a2 + hstep, voffA);
;             PG8_WAIT_V(8); PG8_WAIT_L(0); PG8_BAR; PG8_MMA(0, 0, At, B0); PG8_MMA(0, 1, At, B1); PG8_BAR; PG8_SCHED;
	s_setprio 1
	v_mfma_f32_16x16x32_bf16 v[60:63], v[176:179], v[208:211], v[60:63]
	v_mfma_f32_16x16x32_bf16 v[56:59], v[184:187], v[208:211], v[56:59]
	v_mfma_f32_16x16x32_bf16 v[52:55], v[176:179], v[216:219], v[52:55]
	v_mfma_f32_16x16x32_bf16 v[44:47], v[184:187], v[216:219], v[44:47]
	v_mfma_f32_16x16x32_bf16 v[36:39], v[176:179], v[224:227], v[36:39]
	v_mfma_f32_16x16x32_bf16 v[28:31], v[184:187], v[224:227], v[28:31]
	v_mfma_f32_16x16x32_bf16 v[20:23], v[176:179], v[232:235], v[20:23]
	v_mfma_f32_16x16x32_bf16 v[12:15], v[184:187], v[232:235], v[12:15]
	v_mfma_f32_16x16x32_bf16 v[60:63], v[180:183], v[212:215], v[60:63]
	v_mfma_f32_16x16x32_bf16 v[56:59], v[188:191], v[212:215], v[56:59]
	v_mfma_f32_16x16x32_bf16 v[52:55], v[180:183], v[220:223], v[52:55]
	v_mfma_f32_16x16x32_bf16 v[44:47], v[188:191], v[220:223], v[44:47]
	v_mfma_f32_16x16x32_bf16 v[36:39], v[180:183], v[228:231], v[36:39]
	v_mfma_f32_16x16x32_bf16 v[28:31], v[188:191], v[228:231], v[28:31]
	v_mfma_f32_16x16x32_bf16 v[20:23], v[180:183], v[236:239], v[20:23]
	v_mfma_f32_16x16x32_bf16 v[12:15], v[188:191], v[236:239], v[12:15]
	s_setprio 0
	s_setprio 1
	v_mfma_f32_16x16x32_bf16 v[48:51], v[192:195], v[208:211], v[48:51]
	v_mfma_f32_16x16x32_bf16 v[40:43], v[200:203], v[208:211], v[40:43]
	v_mfma_f32_16x16x32_bf16 v[32:35], v[192:195], v[216:219], v[32:35]
	v_mfma_f32_16x16x32_bf16 v[24:27], v[200:203], v[216:219], v[24:27]
	v_mfma_f32_16x16x32_bf16 v[16:19], v[192:195], v[224:227], v[16:19]
	v_mfma_f32_16x16x32_bf16 v[8:11], v[200:203], v[224:227], v[8:11]
	v_mfma_f32_16x16x32_bf16 v[4:7], v[192:195], v[232:235], v[4:7]
	v_mfma_f32_16x16x32_bf16 v[0:3], v[200:203], v[232:235], v[0:3]
	v_mfma_f32_16x16x32_bf16 v[48:51], v[196:199], v[212:215], v[48:51]
	v_mfma_f32_16x16x32_bf16 v[40:43], v[204:207], v[212:215], v[40:43]
	v_mfma_f32_16x16x32_bf16 v[32:35], v[196:199], v[220:223], v[32:35]
	v_mfma_f32_16x16x32_bf16 v[24:27], v[204:207], v[220:223], v[24:27]
	v_mfma_f32_16x16x32_bf16 v[16:19], v[196:199], v[228:231], v[16:19]
	v_mfma_f32_16x16x32_bf16 v[8:11], v[204:207], v[228:231], v[8:11]
	v_mfma_f32_16x16x32_bf16 v[4:7], v[196:199], v[236:239], v[4:7]
	v_mfma_f32_16x16x32_bf16 v[0:3], v[204:207], v[236:239], v[0:3]
	s_setprio 0
	s_barrier
	s_add_i32 s3, 0, 0x18000
	v_add_u32_e32 v169, s3, v166
	s_add_i32 s8, 0, 0x1c000
	ds_read_b128 v[176:179], v169
	ds_read_b128 v[180:183], v169 offset:1024
	ds_read_b128 v[184:187], v169 offset:2048
	ds_read_b128 v[188:191], v169 offset:3072
	v_add_u32_e32 v169, s8, v166
	ds_read_b128 v[192:195], v169
	ds_read_b128 v[196:199], v169 offset:1024
	ds_read_b128 v[200:203], v169 offset:2048
	ds_read_b128 v[204:207], v169 offset:3072
	v_lshl_add_u64 v[240:241], v[240:241], 0, s[74:75]
	s_mov_b32 m0, s16
	v_lshl_add_u64 v[250:251], v[240:241], 0, v[148:149]
	ds_read_b128 v[208:211], v168 offset:32768
	ds_read_b128 v[212:215], v168 offset:33792
	ds_read_b128 v[216:219], v168 offset:34816
	ds_read_b128 v[220:223], v168 offset:35840
	ds_read_b128 v[224:227], v168 offset:36864
	ds_read_b128 v[228:231], v168 offset:37888
	ds_read_b128 v[232:235], v168 offset:38912
	ds_read_b128 v[236:239], v168 offset:39936
	global_load_lds_dwordx4 v[250:251], off
	v_lshl_add_u64 v[240:241], v[240:241], 0, v[146:147]
	s_mov_b32 m0, s17
	s_nop 0
	global_load_lds_dwordx4 v[240:241], off
	s_waitcnt vmcnt(8) lgkmcnt(0)
	s_barrier
	s_setprio 1
	v_mfma_f32_16x16x32_bf16 v[124:127], v[176:179], v[208:211], v[124:127]
	v_mfma_f32_16x16x32_bf16 v[120:123], v[184:187], v[208:211], v[120:123]
	v_mfma_f32_16x16x32_bf16 v[116:119], v[176:179], v[216:219], v[116:119]
	v_mfma_f32_16x16x32_bf16 v[108:111], v[184:187], v[216:219], v[108:111]
	v_mfma_f32_16x16x32_bf16 v[100:103], v[176:179], v[224:227], v[100:103]
	v_mfma_f32_16x16x32_bf16 v[92:95], v[184:187], v[224:227], v[92:95]
	v_mfma_f32_16x16x32_bf16 v[84:87], v[176:179], v[232:235], v[84:87]
	v_mfma_f32_16x16x32_bf16 v[76:79], v[184:187], v[232:235], v[76:79]
	v_mfma_f32_16x16x32_bf16 v[124:127], v[180:183], v[212:215], v[124:127]
	v_mfma_f32_16x16x32_bf16 v[120:123], v[188:191], v[212:215], v[120:123]
	v_mfma_f32_16x16x32_bf16 v[116:119], v[180:183], v[220:223], v[116:119]
	v_mfma_f32_16x16x32_bf16 v[108:111], v[188:191], v[220:223], v[108:111]
	v_mfma_f32_16x16x32_bf16 v[100:103], v[180:183], v[228:231], v[100:103]
	v_mfma_f32_16x16x32_bf16 v[92:95], v[188:191], v[228:231], v[92:95]
	v_mfma_f32_16x16x32_bf16 v[84:87], v[180:183], v[236:239], v[84:87]
	v_mfma_f32_16x16x32_bf16 v[76:79], v[188:191], v[236:239], v[76:79]
	s_setprio 0
	s_setprio 1
	v_mfma_f32_16x16x32_bf16 v[112:115], v[192:195], v[208:211], v[112:115]
	v_mfma_f32_16x16x32_bf16 v[104:107], v[200:203], v[208:211], v[104:107]
	v_mfma_f32_16x16x32_bf16 v[96:99], v[192:195], v[216:219], v[96:99]
	v_mfma_f32_16x16x32_bf16 v[88:91], v[200:203], v[216:219], v[88:91]
	v_mfma_f32_16x16x32_bf16 v[80:83], v[192:195], v[224:227], v[80:83]
	v_mfma_f32_16x16x32_bf16 v[72:75], v[200:203], v[224:227], v[72:75]
	v_mfma_f32_16x16x32_bf16 v[68:71], v[192:195], v[232:235], v[68:71]
	v_mfma_f32_16x16x32_bf16 v[64:67], v[200:203], v[232:235], v[64:67]
	v_mfma_f32_16x16x32_bf16 v[112:115], v[196:199], v[212:215], v[112:115]
	v_mfma_f32_16x16x32_bf16 v[104:107], v[204:207], v[212:215], v[104:107]
	v_mfma_f32_16x16x32_bf16 v[96:99], v[196:199], v[220:223], v[96:99]
	v_mfma_f32_16x16x32_bf16 v[88:91], v[204:207], v[220:223], v[88:91]
	v_mfma_f32_16x16x32_bf16 v[80:83], v[196:199], v[228:231], v[80:83]
	v_mfma_f32_16x16x32_bf16 v[72:75], v[204:207], v[228:231], v[72:75]
	v_mfma_f32_16x16x32_bf16 v[68:71], v[196:199], v[236:239], v[68:71]
	v_mfma_f32_16x16x32_bf16 v[64:67], v[204:207], v[236:239], v[64:67]
	s_setprio 0
	s_barrier
; #define PG8_STAGE(bufoff, gbase, voff) do { _Pragma("unroll") for (int _i = 0; _i < 2; ++_i) \
;         __builtin_amdgcn_global_load_lds((const unsigned*)((const char*)(gbase) + (voff)[_i]), (PG8_LAS unsigned*)(lds + (bufoff) + ldsw + _i * 8192), 16, 0, 0); } while (0)
; #define PG8_LDA(dst, b, h) do { _Pragma("unroll") for (int m = 0; m < 4; ++m) _Pragma("unroll") for (int k = 0; k < 2; ++k) dst[m][k] = *(const PG8_LAS bf16x8*)(lds + PG8_SA(b, h) + aoff + m * 2048 + k * 1024); } while (0)
; #define PG8_MMA(ai, bj, At, Bt) do { __builtin_amdgcn_s_setprio(1); _Pragma("unroll") for (int m = 0; m < 4; ++m) _Pragma("unroll") for (int n = 0; n < 2; ++n) _Pragma("unroll") for (int k = 0; k < 2; ++k) \
;         acc[ai][bj][m][n] = __builtin_amdgcn_mfma_f32_16x16x32_bf16(Bt[n][k], At[m][k], acc[ai][bj][m][n], 0, 0, 0); __builtin_amdgcn_s_setprio(0); } while (0)
; #define PG8_WAIT_V(n) asm volatile("s_waitcnt vmcnt(" #n ")" ::: "memory")
; #define PG8_WAIT_L(n) asm volatile("s_waitcnt lgkmcnt(" #n ")" ::: "memory")
; #define PG8_BAR __builtin_amdgcn_s_barrier()
; #define PG8_SCHED __builtin_amdgcn_sched_barrier(0)
; template <class Epi, class Sched, bool ALIGN_EPI = false, bool SP2 = false>
; __device__ __forceinline__ void gemm_phase(PG8_LAS unsigned char* lds, const Gemm g, const Sched& S, const Epi& E, int tid_in) {
;     ...
;         for (int t = 0; t < nt; t += 2) {
;             const bool last = (t == nt - 2);
;             const char* a1 = cA + (size_t)(t + 1) * kstep;
;             const char* a2 = last ? nA : cA + (size_t)(t + 2) * kstep; const char* b2 = last ? nB : cB + (size_t)(t + 2) * kstep;
;             const char* a3 = a2 + kstep; const char* b3 = b2 + kstep;
;     ...
;             PG8_LDA(At, 1, 1); PG8_STAGE(PG8_SB(1, 0), b3, voffB); PG8_STAGE(PG8_SB(1, 1), b3 + hstep, voffB); PG8_STAGE(PG8_SA(1, 0), a3, voffA);
;             PG8_WAIT_V(8); PG8_WAIT_L(0); PG8_BAR; PG8_MMA(1, 0, At, B0); PG8_MMA(1, 1, At, B1); PG8_BAR; PG8_SCHED;
;     ...
;         if constexpr (ALIGN_EPI) { if (wr == 0) PG8_BAR; }
	s_add_i32 s3, s3, s1
	v_lshl_add_u64 v[162:163], v[162:163], 0, s[70:71]
	s_mov_b32 m0, s3
	ds_read_b128 v[208:211], v168 offset:49152
	ds_read_b128 v[212:215], v168 offset:50176
	ds_read_b128 v[216:219], v168 offset:51200
	ds_read_b128 v[220:223], v168 offset:52224
	ds_read_b128 v[224:227], v168 offset:53248
	ds_read_b128 v[228:231], v168 offset:54272
	ds_read_b128 v[232:235], v168 offset:55296
	ds_read_b128 v[236:239], v168 offset:56320
	global_load_lds_dwordx4 v[162:163], off
	v_lshl_add_u64 v[162:163], v[244:245], 0, s[70:71]
	s_add_i32 m0, s3, 0x2000
	s_add_i32 s3, s8, s1
	global_load_lds_dwordx4 v[162:163], off
	v_lshl_add_u64 v[162:163], v[242:243], 0, s[60:61]
	v_lshl_add_u64 v[240:241], v[162:163], 0, v[128:129]
	s_mov_b32 m0, s3
	v_lshl_add_u64 v[162:163], v[162:163], 0, v[144:145]
	global_load_lds_dwordx4 v[240:241], off
	s_add_i32 m0, s3, 0x2000
	s_nop 0
	global_load_lds_dwordx4 v[162:163], off
	v_lshl_add_u64 v[162:163], v[246:247], 0, s[70:71]
	s_mov_b32 m0, s18
	s_nop 0
	global_load_lds_dwordx4 v[162:163], off
	v_lshl_add_u64 v[162:163], v[248:249], 0, s[70:71]
	s_mov_b32 m0, s19
	s_nop 0
	global_load_lds_dwordx4 v[162:163], off
	s_waitcnt vmcnt(8) lgkmcnt(0)
	s_barrier
	s_setprio 1
	v_mfma_f32_16x16x32_bf16 v[60:63], v[176:179], v[208:211], v[60:63]
	v_mfma_f32_16x16x32_bf16 v[56:59], v[184:187], v[208:211], v[56:59]
	v_mfma_f32_16x16x32_bf16 v[52:55], v[176:179], v[216:219], v[52:55]
	v_mfma_f32_16x16x32_bf16 v[44:47], v[184:187], v[216:219], v[44:47]
	v_mfma_f32_16x16x32_bf16 v[36:39], v[176:179], v[224:227], v[36:39]
	v_mfma_f32_16x16x32_bf16 v[28:31], v[184:187], v[224:227], v[28:31]
	v_mfma_f32_16x16x32_bf16 v[20:23], v[176:179], v[232:235], v[20:23]
	v_mfma_f32_16x16x32_bf16 v[12:15], v[184:187], v[232:235], v[12:15]
	v_mfma_f32_16x16x32_bf16 v[60:63], v[180:183], v[212:215], v[60:63]
	v_mfma_f32_16x16x32_bf16 v[56:59], v[188:191], v[212:215], v[56:59]
	v_mfma_f32_16x16x32_bf16 v[52:55], v[180:183], v[220:223], v[52:55]
	v_mfma_f32_16x16x32_bf16 v[44:47], v[188:191], v[220:223], v[44:47]
	v_mfma_f32_16x16x32_bf16 v[36:39], v[180:183], v[228:231], v[36:39]
	v_mfma_f32_16x16x32_bf16 v[28:31], v[188:191], v[228:231], v[28:31]
	v_mfma_f32_16x16x32_bf16 v[20:23], v[180:183], v[236:239], v[20:23]
	v_mfma_f32_16x16x32_bf16 v[12:15], v[188:191], v[236:239], v[12:15]
	s_setprio 0
	s_setprio 1
	v_mfma_f32_16x16x32_bf16 v[48:51], v[192:195], v[208:211], v[48:51]
	v_mfma_f32_16x16x32_bf16 v[40:43], v[200:203], v[208:211], v[40:43]
	v_mfma_f32_16x16x32_bf16 v[32:35], v[192:195], v[216:219], v[32:35]
	v_mfma_f32_16x16x32_bf16 v[24:27], v[200:203], v[216:219], v[24:27]
	v_mfma_f32_16x16x32_bf16 v[16:19], v[192:195], v[224:227], v[16:19]
	v_mfma_f32_16x16x32_bf16 v[8:11], v[200:203], v[224:227], v[8:11]
	v_mfma_f32_16x16x32_bf16 v[4:7], v[192:195], v[232:235], v[4:7]
	v_mfma_f32_16x16x32_bf16 v[0:3], v[200:203], v[232:235], v[0:3]
	v_mfma_f32_16x16x32_bf16 v[48:51], v[196:199], v[212:215], v[48:51]
	v_mfma_f32_16x16x32_bf16 v[40:43], v[204:207], v[212:215], v[40:43]
	v_mfma_f32_16x16x32_bf16 v[32:35], v[196:199], v[220:223], v[32:35]
	v_mfma_f32_16x16x32_bf16 v[24:27], v[204:207], v[220:223], v[24:27]
	v_mfma_f32_16x16x32_bf16 v[16:19], v[196:199], v[228:231], v[16:19]
	v_mfma_f32_16x16x32_bf16 v[8:11], v[204:207], v[228:231], v[8:11]
	v_mfma_f32_16x16x32_bf16 v[4:7], v[196:199], v[236:239], v[4:7]
	v_mfma_f32_16x16x32_bf16 v[0:3], v[204:207], v[236:239], v[0:3]
	s_setprio 0
	s_barrier
	s_add_i32 s2, s2, 2
	v_lshl_add_u64 v[160:161], v[160:161], 0, s[82:83]
	s_cmpk_gt_u32 s2, 0x55
	v_mov_b64_e32 v[162:163], v[164:165]
	s_cbranch_scc0 .LBB0_683
	s_and_b64 vcc, exec, s[12:13]
	s_cbranch_vccz .LBB0_686
	s_barrier
